# v06 (v05 + gla_prep LDS reads pipelined) + removed redundant s_setprio 0/1 pairs in the middle of each 32-MFMA block (24 sites)
# speedup vs baseline: 1.0013x; 1.0013x over previous
.LBB0_104:
	s_add_u32 s10, s8, 0xfff00080
	s_addc_u32 s11, s9, -1
	s_add_i32 s34, 0, 0x10000
	s_cmp_eq_u32 s29, 60
	s_cselect_b32 s13, s7, s11
	s_cselect_b32 s12, s24, s10
	s_cselect_b32 s11, s25, s28
	s_cselect_b32 s10, s26, s27
	s_add_i32 s40, 0, 0x14000
	v_add_u32_e32 v158, s34, v162
	v_add_u32_e32 v172, s40, v162
	s_waitcnt lgkmcnt(0)
	ds_read_b128 v[132:135], v158
	ds_read_b128 v[136:139], v158 offset:1024
	ds_read_b128 v[154:157], v158 offset:2048
	ds_read_b128 v[158:161], v158 offset:3072
	ds_read_b128 v[184:187], v172
	ds_read_b128 v[188:191], v172 offset:1024
	ds_read_b128 v[192:195], v172 offset:2048
	ds_read_b128 v[196:199], v172 offset:3072
	v_lshl_add_u64 v[216:217], s[8:9], 0, v[150:151]
	s_add_i32 m0, s16, 0xc000
	ds_read_b128 v[200:203], v182
	ds_read_b128 v[204:207], v182 offset:1024
	ds_read_b128 v[208:211], v182 offset:2048
	ds_read_b128 v[212:215], v182 offset:3072
	ds_read_b128 v[232:235], v182 offset:4096
	ds_read_b128 v[236:239], v182 offset:5120
	ds_read_b128 v[240:243], v182 offset:6144
	ds_read_b128 v[244:247], v182 offset:7168
	global_load_lds_dwordx4 v[216:217], off
	v_lshl_add_u64 v[216:217], s[8:9], 0, v[152:153]
	s_add_i32 m0, s16, 0xe000
	s_nop 0
	global_load_lds_dwordx4 v[216:217], off
	s_waitcnt vmcnt(8)
	s_waitcnt lgkmcnt(0)
	s_barrier
	s_setprio 1
	s_waitcnt lgkmcnt(0)
	v_mfma_f32_16x16x32_bf16 v[128:131], v[132:135], v[200:203], v[128:131]
	v_mfma_f32_16x16x32_bf16 v[124:127], v[154:157], v[200:203], v[124:127]
	v_mfma_f32_16x16x32_bf16 v[112:115], v[132:135], v[208:211], v[112:115]
	v_mfma_f32_16x16x32_bf16 v[108:111], v[154:157], v[208:211], v[108:111]
	v_mfma_f32_16x16x32_bf16 v[96:99], v[132:135], v[232:235], v[96:99]
	v_mfma_f32_16x16x32_bf16 v[92:95], v[154:157], v[232:235], v[92:95]
	v_mfma_f32_16x16x32_bf16 v[80:83], v[132:135], v[240:243], v[80:83]
	v_mfma_f32_16x16x32_bf16 v[76:79], v[154:157], v[240:243], v[76:79]
	v_mfma_f32_16x16x32_bf16 v[128:131], v[136:139], v[204:207], v[128:131]
	v_mfma_f32_16x16x32_bf16 v[124:127], v[158:161], v[204:207], v[124:127]
	v_mfma_f32_16x16x32_bf16 v[112:115], v[136:139], v[212:215], v[112:115]
	v_mfma_f32_16x16x32_bf16 v[108:111], v[158:161], v[212:215], v[108:111]
	v_mfma_f32_16x16x32_bf16 v[96:99], v[136:139], v[236:239], v[96:99]
	v_mfma_f32_16x16x32_bf16 v[92:95], v[158:161], v[236:239], v[92:95]
	v_mfma_f32_16x16x32_bf16 v[80:83], v[136:139], v[244:247], v[80:83]
	v_mfma_f32_16x16x32_bf16 v[76:79], v[158:161], v[244:247], v[76:79]
	v_mfma_f32_16x16x32_bf16 v[120:123], v[184:187], v[200:203], v[120:123]
	v_mfma_f32_16x16x32_bf16 v[116:119], v[192:195], v[200:203], v[116:119]
	v_mfma_f32_16x16x32_bf16 v[104:107], v[184:187], v[208:211], v[104:107]
	v_mfma_f32_16x16x32_bf16 v[100:103], v[192:195], v[208:211], v[100:103]
	v_mfma_f32_16x16x32_bf16 v[88:91], v[184:187], v[232:235], v[88:91]
	v_mfma_f32_16x16x32_bf16 v[84:87], v[192:195], v[232:235], v[84:87]
	v_mfma_f32_16x16x32_bf16 v[72:75], v[184:187], v[240:243], v[72:75]
	v_mfma_f32_16x16x32_bf16 v[68:71], v[192:195], v[240:243], v[68:71]
	v_mfma_f32_16x16x32_bf16 v[120:123], v[188:191], v[204:207], v[120:123]
	v_mfma_f32_16x16x32_bf16 v[116:119], v[196:199], v[204:207], v[116:119]
	v_mfma_f32_16x16x32_bf16 v[104:107], v[188:191], v[212:215], v[104:107]
	v_mfma_f32_16x16x32_bf16 v[100:103], v[196:199], v[212:215], v[100:103]
	v_mfma_f32_16x16x32_bf16 v[88:91], v[188:191], v[236:239], v[88:91]
	v_mfma_f32_16x16x32_bf16 v[84:87], v[196:199], v[236:239], v[84:87]
	v_mfma_f32_16x16x32_bf16 v[72:75], v[188:191], v[244:247], v[72:75]
	v_mfma_f32_16x16x32_bf16 v[68:71], v[196:199], v[244:247], v[68:71]
	s_setprio 0
	s_barrier
	s_add_i32 s34, s34, s15
	v_lshl_add_u64 v[216:217], s[10:11], 0, v[142:143]
	s_mov_b32 m0, s34
	ds_read_b128 v[200:203], v182 offset:16384
	ds_read_b128 v[204:207], v182 offset:17408
	ds_read_b128 v[208:211], v182 offset:18432
	ds_read_b128 v[212:215], v182 offset:19456
	ds_read_b128 v[232:235], v182 offset:20480
	ds_read_b128 v[236:239], v182 offset:21504
	ds_read_b128 v[240:243], v182 offset:22528
	ds_read_b128 v[244:247], v182 offset:23552
	global_load_lds_dwordx4 v[216:217], off
	s_add_i32 m0, s34, 0x2000
	s_add_u32 s34, s10, 0x100000
	v_lshl_add_u64 v[220:221], s[10:11], 0, v[146:147]
	s_addc_u32 s35, s11, 0
	s_add_i32 s40, s40, s15
	global_load_lds_dwordx4 v[220:221], off
	v_lshl_add_u64 v[172:173], s[34:35], 0, v[142:143]
	s_mov_b32 m0, s40
	v_lshl_add_u64 v[174:175], s[12:13], 0, v[144:145]
	global_load_lds_dwordx4 v[172:173], off
	v_lshl_add_u64 v[172:173], s[34:35], 0, v[146:147]
	s_add_i32 m0, s40, 0x2000
	s_nop 0
	global_load_lds_dwordx4 v[172:173], off
	v_lshl_add_u64 v[172:173], s[12:13], 0, v[140:141]
	s_mov_b32 m0, s16
	s_nop 0
	global_load_lds_dwordx4 v[172:173], off
	s_mov_b32 m0, s17
	s_nop 0
	global_load_lds_dwordx4 v[174:175], off
	s_waitcnt vmcnt(8)
	s_waitcnt lgkmcnt(0)
	s_barrier
	s_setprio 1
	s_waitcnt lgkmcnt(0)
	v_mfma_f32_16x16x32_bf16 v[64:67], v[132:135], v[200:203], v[64:67]
	v_mfma_f32_16x16x32_bf16 v[60:63], v[154:157], v[200:203], v[60:63]
	v_mfma_f32_16x16x32_bf16 v[48:51], v[132:135], v[208:211], v[48:51]
	v_mfma_f32_16x16x32_bf16 v[44:47], v[154:157], v[208:211], v[44:47]
	v_mfma_f32_16x16x32_bf16 v[30:33], v[132:135], v[232:235], v[30:33]
	v_mfma_f32_16x16x32_bf16 v[26:29], v[154:157], v[232:235], v[26:29]
	v_mfma_f32_16x16x32_bf16 v[14:17], v[132:135], v[240:243], v[14:17]
	v_mfma_f32_16x16x32_bf16 v[10:13], v[154:157], v[240:243], v[10:13]
	v_mfma_f32_16x16x32_bf16 v[64:67], v[136:139], v[204:207], v[64:67]
	v_mfma_f32_16x16x32_bf16 v[60:63], v[158:161], v[204:207], v[60:63]
	v_mfma_f32_16x16x32_bf16 v[48:51], v[136:139], v[212:215], v[48:51]
	v_mfma_f32_16x16x32_bf16 v[44:47], v[158:161], v[212:215], v[44:47]
	v_mfma_f32_16x16x32_bf16 v[30:33], v[136:139], v[236:239], v[30:33]
	v_mfma_f32_16x16x32_bf16 v[26:29], v[158:161], v[236:239], v[26:29]
	v_mfma_f32_16x16x32_bf16 v[14:17], v[136:139], v[244:247], v[14:17]
	v_mfma_f32_16x16x32_bf16 v[10:13], v[158:161], v[244:247], v[10:13]
	v_mfma_f32_16x16x32_bf16 v[56:59], v[184:187], v[200:203], v[56:59]
	v_mfma_f32_16x16x32_bf16 v[52:55], v[192:195], v[200:203], v[52:55]
	v_mfma_f32_16x16x32_bf16 v[40:43], v[184:187], v[208:211], v[40:43]
	v_mfma_f32_16x16x32_bf16 v[36:39], v[192:195], v[208:211], v[36:39]
	v_mfma_f32_16x16x32_bf16 v[22:25], v[184:187], v[232:235], v[22:25]
	v_mfma_f32_16x16x32_bf16 v[18:21], v[192:195], v[232:235], v[18:21]
	v_mfma_f32_16x16x32_bf16 v[6:9], v[184:187], v[240:243], v[6:9]
	v_mfma_f32_16x16x32_bf16 v[2:5], v[192:195], v[240:243], v[2:5]
	v_mfma_f32_16x16x32_bf16 v[56:59], v[188:191], v[204:207], v[56:59]
	v_mfma_f32_16x16x32_bf16 v[52:55], v[196:199], v[204:207], v[52:55]
	v_mfma_f32_16x16x32_bf16 v[40:43], v[188:191], v[212:215], v[40:43]
	v_mfma_f32_16x16x32_bf16 v[36:39], v[196:199], v[212:215], v[36:39]
	v_mfma_f32_16x16x32_bf16 v[22:25], v[188:191], v[236:239], v[22:25]
	v_mfma_f32_16x16x32_bf16 v[18:21], v[196:199], v[236:239], v[18:21]
	v_mfma_f32_16x16x32_bf16 v[6:9], v[188:191], v[244:247], v[6:9]
	v_mfma_f32_16x16x32_bf16 v[2:5], v[196:199], v[244:247], v[2:5]
	s_setprio 0
	s_barrier
	s_add_i32 s34, 0, 0x18000
	s_add_i32 s35, 0, 0x1c000
	v_add_u32_e32 v158, s34, v162
	v_add_u32_e32 v176, s35, v162
	ds_read_b128 v[132:135], v158
	ds_read_b128 v[136:139], v158 offset:1024
	ds_read_b128 v[154:157], v158 offset:2048
	ds_read_b128 v[158:161], v158 offset:3072
	ds_read_b128 v[184:187], v176
	ds_read_b128 v[188:191], v176 offset:1024
	ds_read_b128 v[192:195], v176 offset:2048
	ds_read_b128 v[196:199], v176 offset:3072
	s_add_u32 s12, s12, 0x100000
	s_addc_u32 s13, s13, 0
	s_mov_b32 m0, s18
	v_lshl_add_u64 v[176:177], s[12:13], 0, v[140:141]
	ds_read_b128 v[200:203], v182 offset:32768
	ds_read_b128 v[204:207], v182 offset:33792
	ds_read_b128 v[208:211], v182 offset:34816
	ds_read_b128 v[212:215], v182 offset:35840
	ds_read_b128 v[232:235], v182 offset:36864
	ds_read_b128 v[236:239], v182 offset:37888
	ds_read_b128 v[240:243], v182 offset:38912
	ds_read_b128 v[244:247], v182 offset:39936
	global_load_lds_dwordx4 v[176:177], off
	v_lshl_add_u64 v[176:177], s[12:13], 0, v[144:145]
	s_mov_b32 m0, s19
	s_nop 0
	global_load_lds_dwordx4 v[176:177], off
	s_waitcnt vmcnt(8)
	s_waitcnt lgkmcnt(0)
	s_barrier
	s_setprio 1
	s_waitcnt lgkmcnt(0)
	v_mfma_f32_16x16x32_bf16 v[128:131], v[132:135], v[200:203], v[128:131]
	v_mfma_f32_16x16x32_bf16 v[124:127], v[154:157], v[200:203], v[124:127]
	v_mfma_f32_16x16x32_bf16 v[112:115], v[132:135], v[208:211], v[112:115]
	v_mfma_f32_16x16x32_bf16 v[108:111], v[154:157], v[208:211], v[108:111]
	v_mfma_f32_16x16x32_bf16 v[96:99], v[132:135], v[232:235], v[96:99]
	v_mfma_f32_16x16x32_bf16 v[92:95], v[154:157], v[232:235], v[92:95]
	v_mfma_f32_16x16x32_bf16 v[80:83], v[132:135], v[240:243], v[80:83]
	v_mfma_f32_16x16x32_bf16 v[76:79], v[154:157], v[240:243], v[76:79]
	v_mfma_f32_16x16x32_bf16 v[128:131], v[136:139], v[204:207], v[128:131]
	v_mfma_f32_16x16x32_bf16 v[124:127], v[158:161], v[204:207], v[124:127]
	v_mfma_f32_16x16x32_bf16 v[112:115], v[136:139], v[212:215], v[112:115]
	v_mfma_f32_16x16x32_bf16 v[108:111], v[158:161], v[212:215], v[108:111]
	v_mfma_f32_16x16x32_bf16 v[96:99], v[136:139], v[236:239], v[96:99]
	v_mfma_f32_16x16x32_bf16 v[92:95], v[158:161], v[236:239], v[92:95]
	v_mfma_f32_16x16x32_bf16 v[80:83], v[136:139], v[244:247], v[80:83]
	v_mfma_f32_16x16x32_bf16 v[76:79], v[158:161], v[244:247], v[76:79]
	v_mfma_f32_16x16x32_bf16 v[120:123], v[184:187], v[200:203], v[120:123]
	v_mfma_f32_16x16x32_bf16 v[116:119], v[192:195], v[200:203], v[116:119]
	v_mfma_f32_16x16x32_bf16 v[104:107], v[184:187], v[208:211], v[104:107]
	v_mfma_f32_16x16x32_bf16 v[100:103], v[192:195], v[208:211], v[100:103]
	v_mfma_f32_16x16x32_bf16 v[88:91], v[184:187], v[232:235], v[88:91]
	v_mfma_f32_16x16x32_bf16 v[84:87], v[192:195], v[232:235], v[84:87]
	v_mfma_f32_16x16x32_bf16 v[72:75], v[184:187], v[240:243], v[72:75]
	v_mfma_f32_16x16x32_bf16 v[68:71], v[192:195], v[240:243], v[68:71]
	v_mfma_f32_16x16x32_bf16 v[120:123], v[188:191], v[204:207], v[120:123]
	v_mfma_f32_16x16x32_bf16 v[116:119], v[196:199], v[204:207], v[116:119]
	v_mfma_f32_16x16x32_bf16 v[104:107], v[188:191], v[212:215], v[104:107]
	v_mfma_f32_16x16x32_bf16 v[100:103], v[196:199], v[212:215], v[100:103]
	v_mfma_f32_16x16x32_bf16 v[88:91], v[188:191], v[236:239], v[88:91]
	v_mfma_f32_16x16x32_bf16 v[84:87], v[196:199], v[236:239], v[84:87]
	v_mfma_f32_16x16x32_bf16 v[72:75], v[188:191], v[244:247], v[72:75]
	v_mfma_f32_16x16x32_bf16 v[68:71], v[196:199], v[244:247], v[68:71]
	s_setprio 0
	s_barrier
	s_add_i32 s12, s34, s15
	v_lshl_add_u64 v[176:177], v[216:217], 0, s[2:3]
	s_mov_b32 m0, s12
	ds_read_b128 v[200:203], v182 offset:49152
	ds_read_b128 v[204:207], v182 offset:50176
	ds_read_b128 v[208:211], v182 offset:51200
	ds_read_b128 v[212:215], v182 offset:52224
	ds_read_b128 v[232:235], v182 offset:53248
	ds_read_b128 v[236:239], v182 offset:54272
	ds_read_b128 v[240:243], v182 offset:55296
	ds_read_b128 v[244:247], v182 offset:56320
	global_load_lds_dwordx4 v[176:177], off
	s_add_i32 m0, s12, 0x2000
	s_add_u32 s10, s10, 0x100080
	v_lshl_add_u64 v[176:177], v[220:221], 0, s[2:3]
	s_addc_u32 s11, s11, 0
	s_add_i32 s12, s35, s15
	global_load_lds_dwordx4 v[176:177], off
	v_lshl_add_u64 v[176:177], s[10:11], 0, v[142:143]
	s_mov_b32 m0, s12
	v_lshl_add_u64 v[172:173], v[172:173], 0, s[2:3]
	global_load_lds_dwordx4 v[176:177], off
	v_lshl_add_u64 v[176:177], s[10:11], 0, v[146:147]
	s_add_i32 m0, s12, 0x2000
	s_nop 0
	global_load_lds_dwordx4 v[176:177], off
	s_mov_b32 m0, s20
	s_nop 0
	global_load_lds_dwordx4 v[172:173], off
	v_lshl_add_u64 v[172:173], v[174:175], 0, s[2:3]
	s_mov_b32 m0, s21
	s_nop 0
	global_load_lds_dwordx4 v[172:173], off
	s_waitcnt vmcnt(8)
	s_waitcnt lgkmcnt(0)
	s_barrier
	s_setprio 1
	s_waitcnt lgkmcnt(0)
	v_mfma_f32_16x16x32_bf16 v[64:67], v[132:135], v[200:203], v[64:67]
	v_mfma_f32_16x16x32_bf16 v[60:63], v[154:157], v[200:203], v[60:63]
	v_mfma_f32_16x16x32_bf16 v[48:51], v[132:135], v[208:211], v[48:51]
	v_mfma_f32_16x16x32_bf16 v[44:47], v[154:157], v[208:211], v[44:47]
	v_mfma_f32_16x16x32_bf16 v[30:33], v[132:135], v[232:235], v[30:33]
	v_mfma_f32_16x16x32_bf16 v[26:29], v[154:157], v[232:235], v[26:29]
	v_mfma_f32_16x16x32_bf16 v[14:17], v[132:135], v[240:243], v[14:17]
	v_mfma_f32_16x16x32_bf16 v[10:13], v[154:157], v[240:243], v[10:13]
	v_mfma_f32_16x16x32_bf16 v[64:67], v[136:139], v[204:207], v[64:67]
	v_mfma_f32_16x16x32_bf16 v[60:63], v[158:161], v[204:207], v[60:63]
	v_mfma_f32_16x16x32_bf16 v[48:51], v[136:139], v[212:215], v[48:51]
	v_mfma_f32_16x16x32_bf16 v[44:47], v[158:161], v[212:215], v[44:47]
	v_mfma_f32_16x16x32_bf16 v[30:33], v[136:139], v[236:239], v[30:33]
	v_mfma_f32_16x16x32_bf16 v[26:29], v[158:161], v[236:239], v[26:29]
	v_mfma_f32_16x16x32_bf16 v[14:17], v[136:139], v[244:247], v[14:17]
	v_mfma_f32_16x16x32_bf16 v[10:13], v[158:161], v[244:247], v[10:13]
	v_mfma_f32_16x16x32_bf16 v[56:59], v[184:187], v[200:203], v[56:59]
	v_mfma_f32_16x16x32_bf16 v[52:55], v[192:195], v[200:203], v[52:55]
	v_mfma_f32_16x16x32_bf16 v[40:43], v[184:187], v[208:211], v[40:43]
	v_mfma_f32_16x16x32_bf16 v[36:39], v[192:195], v[208:211], v[36:39]
	v_mfma_f32_16x16x32_bf16 v[22:25], v[184:187], v[232:235], v[22:25]
	v_mfma_f32_16x16x32_bf16 v[18:21], v[192:195], v[232:235], v[18:21]
	v_mfma_f32_16x16x32_bf16 v[6:9], v[184:187], v[240:243], v[6:9]
	v_mfma_f32_16x16x32_bf16 v[2:5], v[192:195], v[240:243], v[2:5]
	v_mfma_f32_16x16x32_bf16 v[56:59], v[188:191], v[204:207], v[56:59]
	v_mfma_f32_16x16x32_bf16 v[52:55], v[196:199], v[204:207], v[52:55]
	v_mfma_f32_16x16x32_bf16 v[40:43], v[188:191], v[212:215], v[40:43]
	v_mfma_f32_16x16x32_bf16 v[36:39], v[196:199], v[212:215], v[36:39]
	v_mfma_f32_16x16x32_bf16 v[22:25], v[188:191], v[236:239], v[22:25]
	v_mfma_f32_16x16x32_bf16 v[18:21], v[196:199], v[236:239], v[18:21]
	v_mfma_f32_16x16x32_bf16 v[6:9], v[188:191], v[244:247], v[6:9]
	v_mfma_f32_16x16x32_bf16 v[2:5], v[196:199], v[244:247], v[2:5]
	s_setprio 0
	s_barrier
	s_add_i32 s29, s29, 2
	s_add_u32 s8, s8, 0x100
	s_addc_u32 s9, s9, 0
	s_add_u32 s27, s27, 0x100
	s_addc_u32 s28, s28, 0
	s_cmp_gt_u32 s29, 61
	s_cbranch_scc0 .LBB0_104
	s_and_b64 vcc, exec, s[66:67]
	s_cbranch_vccnz .LBB0_109
	v_lshl_add_u32 v154, s6, 8, v35
	s_cmp_gt_i32 s76, 7
	s_mov_b64 s[6:7], -1
	s_cbranch_scc1 .LBB0_110

.LBB0_200:
	s_add_u32 s10, s8, 0xfff80080
	s_addc_u32 s11, s9, -1
	s_add_i32 s35, 0, 0x10000
	s_cmp_eq_u32 s34, 28
	s_cselect_b32 s13, s7, s11
	s_cselect_b32 s12, s26, s10
	s_cselect_b32 s11, s27, s31
	s_cselect_b32 s10, s28, s29
	s_add_i32 s40, 0, 0x14000
	v_add_u32_e32 v2, s35, v194
	v_add_u32_e32 v14, s40, v194
	ds_read_b128 v[18:21], v2
	ds_read_b128 v[22:25], v2 offset:1024
	ds_read_b128 v[26:29], v2 offset:2048
	ds_read_b128 v[30:33], v2 offset:3072
	ds_read_b128 v[2:5], v14
	ds_read_b128 v[6:9], v14 offset:1024
	ds_read_b128 v[10:13], v14 offset:2048
	ds_read_b128 v[14:17], v14 offset:3072
	v_lshl_add_u64 v[196:197], s[8:9], 0, v[182:183]
	s_add_i32 m0, s18, 0xc000
	ds_read_b128 v[186:189], v206
	ds_read_b128 v[190:193], v206 offset:1024
	ds_read_b128 v[208:211], v206 offset:2048
	ds_read_b128 v[212:215], v206 offset:3072
	ds_read_b128 v[232:235], v206 offset:4096
	ds_read_b128 v[236:239], v206 offset:5120
	ds_read_b128 v[240:243], v206 offset:6144
	ds_read_b128 v[244:247], v206 offset:7168
	global_load_lds_dwordx4 v[196:197], off
	v_lshl_add_u64 v[196:197], s[8:9], 0, v[184:185]
	s_add_i32 m0, s18, 0xe000
	s_nop 0
	global_load_lds_dwordx4 v[196:197], off
	s_waitcnt vmcnt(8)
	s_waitcnt lgkmcnt(0)
	s_barrier
	s_setprio 1
	s_waitcnt lgkmcnt(0)
	v_mfma_f32_16x16x128_f8f6f4 v[160:163], v[18:25], v[186:193], v[160:163]
	v_mfma_f32_16x16x128_f8f6f4 v[156:159], v[26:33], v[186:193], v[156:159]
	v_mfma_f32_16x16x128_f8f6f4 v[144:147], v[18:25], v[208:215], v[144:147]
	v_mfma_f32_16x16x128_f8f6f4 v[140:143], v[26:33], v[208:215], v[140:143]
	v_mfma_f32_16x16x128_f8f6f4 v[128:131], v[18:25], v[232:239], v[128:131]
	v_mfma_f32_16x16x128_f8f6f4 v[124:127], v[26:33], v[232:239], v[124:127]
	v_mfma_f32_16x16x128_f8f6f4 v[112:115], v[18:25], v[240:247], v[112:115]
	v_mfma_f32_16x16x128_f8f6f4 v[108:111], v[26:33], v[240:247], v[108:111]
	v_mfma_f32_16x16x128_f8f6f4 v[152:155], v[2:9], v[186:193], v[152:155]
	v_mfma_f32_16x16x128_f8f6f4 v[148:151], v[10:17], v[186:193], v[148:151]
	v_mfma_f32_16x16x128_f8f6f4 v[136:139], v[2:9], v[208:215], v[136:139]
	v_mfma_f32_16x16x128_f8f6f4 v[132:135], v[10:17], v[208:215], v[132:135]
	v_mfma_f32_16x16x128_f8f6f4 v[120:123], v[2:9], v[232:239], v[120:123]
	v_mfma_f32_16x16x128_f8f6f4 v[116:119], v[10:17], v[232:239], v[116:119]
	v_mfma_f32_16x16x128_f8f6f4 v[104:107], v[2:9], v[240:247], v[104:107]
	v_mfma_f32_16x16x128_f8f6f4 v[100:103], v[10:17], v[240:247], v[100:103]
	s_setprio 0
	s_barrier
	s_add_i32 s35, s35, s15
	v_lshl_add_u64 v[186:187], s[10:11], 0, v[174:175]
	s_mov_b32 m0, s35
	ds_read_b128 v[208:211], v206 offset:16384
	ds_read_b128 v[212:215], v206 offset:17408
	ds_read_b128 v[232:235], v206 offset:18432
	ds_read_b128 v[236:239], v206 offset:19456
	ds_read_b128 v[240:243], v206 offset:20480
	ds_read_b128 v[244:247], v206 offset:21504
	ds_read_b128 v[196:199], v206 offset:22528
	ds_read_b128 v[200:203], v206 offset:23552
	global_load_lds_dwordx4 v[186:187], off
	s_add_i32 m0, s35, 0x2000
	s_add_u32 s76, s10, 0x80000
	v_lshl_add_u64 v[188:189], s[10:11], 0, v[178:179]
	s_addc_u32 s77, s11, 0
	s_add_i32 s35, s40, s15
	global_load_lds_dwordx4 v[188:189], off
	v_lshl_add_u64 v[190:191], s[76:77], 0, v[174:175]
	s_mov_b32 m0, s35
	v_lshl_add_u64 v[192:193], s[12:13], 0, v[176:177]
	global_load_lds_dwordx4 v[190:191], off
	v_lshl_add_u64 v[190:191], s[76:77], 0, v[178:179]
	s_add_i32 m0, s35, 0x2000
	s_nop 0
	global_load_lds_dwordx4 v[190:191], off
	v_lshl_add_u64 v[190:191], s[12:13], 0, v[172:173]
	s_mov_b32 m0, s18
	s_nop 0
	global_load_lds_dwordx4 v[190:191], off
	s_mov_b32 m0, s19
	s_nop 0
	global_load_lds_dwordx4 v[192:193], off
	s_waitcnt vmcnt(8)
	s_waitcnt lgkmcnt(0)
	s_barrier
	s_setprio 1
	s_waitcnt lgkmcnt(0)
	v_mfma_f32_16x16x128_f8f6f4 v[96:99], v[18:25], v[208:215], v[96:99]
	v_mfma_f32_16x16x128_f8f6f4 v[92:95], v[26:33], v[208:215], v[92:95]
	v_mfma_f32_16x16x128_f8f6f4 v[80:83], v[18:25], v[232:239], v[80:83]
	v_mfma_f32_16x16x128_f8f6f4 v[76:79], v[26:33], v[232:239], v[76:79]
	v_mfma_f32_16x16x128_f8f6f4 v[64:67], v[18:25], v[240:247], v[64:67]
	v_mfma_f32_16x16x128_f8f6f4 v[60:63], v[26:33], v[240:247], v[60:63]
	v_mfma_f32_16x16x128_f8f6f4 v[48:51], v[18:25], v[196:203], v[48:51]
	v_mfma_f32_16x16x128_f8f6f4 v[44:47], v[26:33], v[196:203], v[44:47]
	v_mfma_f32_16x16x128_f8f6f4 v[88:91], v[2:9], v[208:215], v[88:91]
	v_mfma_f32_16x16x128_f8f6f4 v[84:87], v[10:17], v[208:215], v[84:87]
	v_mfma_f32_16x16x128_f8f6f4 v[72:75], v[2:9], v[232:239], v[72:75]
	v_mfma_f32_16x16x128_f8f6f4 v[68:71], v[10:17], v[232:239], v[68:71]
	v_mfma_f32_16x16x128_f8f6f4 v[56:59], v[2:9], v[240:247], v[56:59]
	v_mfma_f32_16x16x128_f8f6f4 v[52:55], v[10:17], v[240:247], v[52:55]
	v_mfma_f32_16x16x128_f8f6f4 v[40:43], v[2:9], v[196:203], v[40:43]
	v_mfma_f32_16x16x128_f8f6f4 v[36:39], v[10:17], v[196:203], v[36:39]
	s_setprio 0
	s_barrier
	s_add_i32 s35, 0, 0x18000
	s_add_i32 s40, 0, 0x1c000
	v_add_u32_e32 v14, s35, v194
	v_add_u32_e32 v30, s40, v194
	ds_read_b128 v[2:5], v14
	ds_read_b128 v[6:9], v14 offset:1024
	ds_read_b128 v[10:13], v14 offset:2048
	ds_read_b128 v[14:17], v14 offset:3072
	ds_read_b128 v[18:21], v30
	ds_read_b128 v[22:25], v30 offset:1024
	ds_read_b128 v[26:29], v30 offset:2048
	ds_read_b128 v[30:33], v30 offset:3072
	s_add_u32 s12, s12, 0x80000
	s_addc_u32 s13, s13, 0
	s_mov_b32 m0, s20
	v_lshl_add_u64 v[216:217], s[12:13], 0, v[172:173]
	ds_read_b128 v[196:199], v206 offset:32768
	ds_read_b128 v[200:203], v206 offset:33792
	ds_read_b128 v[208:211], v206 offset:34816
	ds_read_b128 v[212:215], v206 offset:35840
	ds_read_b128 v[232:235], v206 offset:36864
	ds_read_b128 v[236:239], v206 offset:37888
	ds_read_b128 v[240:243], v206 offset:38912
	ds_read_b128 v[244:247], v206 offset:39936
	global_load_lds_dwordx4 v[216:217], off
	v_lshl_add_u64 v[216:217], s[12:13], 0, v[176:177]
	s_mov_b32 m0, s21
	s_nop 0
	global_load_lds_dwordx4 v[216:217], off
	s_waitcnt vmcnt(8)
	s_waitcnt lgkmcnt(0)
	s_barrier
	s_setprio 1
	s_waitcnt lgkmcnt(0)
	v_mfma_f32_16x16x128_f8f6f4 v[160:163], v[2:9], v[196:203], v[160:163]
	v_mfma_f32_16x16x128_f8f6f4 v[156:159], v[10:17], v[196:203], v[156:159]
	v_mfma_f32_16x16x128_f8f6f4 v[144:147], v[2:9], v[208:215], v[144:147]
	v_mfma_f32_16x16x128_f8f6f4 v[140:143], v[10:17], v[208:215], v[140:143]
	v_mfma_f32_16x16x128_f8f6f4 v[128:131], v[2:9], v[232:239], v[128:131]
	v_mfma_f32_16x16x128_f8f6f4 v[124:127], v[10:17], v[232:239], v[124:127]
	v_mfma_f32_16x16x128_f8f6f4 v[112:115], v[2:9], v[240:247], v[112:115]
	v_mfma_f32_16x16x128_f8f6f4 v[108:111], v[10:17], v[240:247], v[108:111]
	v_mfma_f32_16x16x128_f8f6f4 v[152:155], v[18:25], v[196:203], v[152:155]
	v_mfma_f32_16x16x128_f8f6f4 v[148:151], v[26:33], v[196:203], v[148:151]
	v_mfma_f32_16x16x128_f8f6f4 v[136:139], v[18:25], v[208:215], v[136:139]
	v_mfma_f32_16x16x128_f8f6f4 v[132:135], v[26:33], v[208:215], v[132:135]
	v_mfma_f32_16x16x128_f8f6f4 v[120:123], v[18:25], v[232:239], v[120:123]
	v_mfma_f32_16x16x128_f8f6f4 v[116:119], v[26:33], v[232:239], v[116:119]
	v_mfma_f32_16x16x128_f8f6f4 v[104:107], v[18:25], v[240:247], v[104:107]
	v_mfma_f32_16x16x128_f8f6f4 v[100:103], v[26:33], v[240:247], v[100:103]
	s_setprio 0
	s_barrier
	s_add_i32 s12, s35, s15
	v_lshl_add_u64 v[186:187], v[186:187], 0, s[2:3]
	s_mov_b32 m0, s12
	ds_read_b128 v[196:199], v206 offset:49152
	ds_read_b128 v[200:203], v206 offset:50176
	ds_read_b128 v[208:211], v206 offset:51200
	ds_read_b128 v[212:215], v206 offset:52224
	ds_read_b128 v[232:235], v206 offset:53248
	ds_read_b128 v[236:239], v206 offset:54272
	ds_read_b128 v[240:243], v206 offset:55296
	ds_read_b128 v[244:247], v206 offset:56320
	global_load_lds_dwordx4 v[186:187], off
	s_add_i32 m0, s12, 0x2000
	s_add_u32 s10, s10, 0x80080
	v_lshl_add_u64 v[186:187], v[188:189], 0, s[2:3]
	s_addc_u32 s11, s11, 0
	s_add_i32 s12, s40, s15
	global_load_lds_dwordx4 v[186:187], off
	v_lshl_add_u64 v[186:187], s[10:11], 0, v[174:175]
	s_mov_b32 m0, s12
	s_nop 0
	global_load_lds_dwordx4 v[186:187], off
	v_lshl_add_u64 v[186:187], s[10:11], 0, v[178:179]
	s_add_i32 m0, s12, 0x2000
	s_nop 0
	global_load_lds_dwordx4 v[186:187], off
	v_lshl_add_u64 v[186:187], v[190:191], 0, s[2:3]
	s_mov_b32 m0, s22
	s_nop 0
	global_load_lds_dwordx4 v[186:187], off
	v_lshl_add_u64 v[186:187], v[192:193], 0, s[2:3]
	s_mov_b32 m0, s23
	s_nop 0
	global_load_lds_dwordx4 v[186:187], off
	s_waitcnt vmcnt(8)
	s_waitcnt lgkmcnt(0)
	s_barrier
	s_setprio 1
	s_waitcnt lgkmcnt(0)
	v_mfma_f32_16x16x128_f8f6f4 v[96:99], v[2:9], v[196:203], v[96:99]
	v_mfma_f32_16x16x128_f8f6f4 v[92:95], v[10:17], v[196:203], v[92:95]
	v_mfma_f32_16x16x128_f8f6f4 v[80:83], v[2:9], v[208:215], v[80:83]
	v_mfma_f32_16x16x128_f8f6f4 v[76:79], v[10:17], v[208:215], v[76:79]
	v_mfma_f32_16x16x128_f8f6f4 v[64:67], v[2:9], v[232:239], v[64:67]
	v_mfma_f32_16x16x128_f8f6f4 v[60:63], v[10:17], v[232:239], v[60:63]
	v_mfma_f32_16x16x128_f8f6f4 v[48:51], v[2:9], v[240:247], v[48:51]
	v_mfma_f32_16x16x128_f8f6f4 v[44:47], v[10:17], v[240:247], v[44:47]
	v_mfma_f32_16x16x128_f8f6f4 v[88:91], v[18:25], v[196:203], v[88:91]
	v_mfma_f32_16x16x128_f8f6f4 v[84:87], v[26:33], v[196:203], v[84:87]
	v_mfma_f32_16x16x128_f8f6f4 v[72:75], v[18:25], v[208:215], v[72:75]
	v_mfma_f32_16x16x128_f8f6f4 v[68:71], v[26:33], v[208:215], v[68:71]
	v_mfma_f32_16x16x128_f8f6f4 v[56:59], v[18:25], v[232:239], v[56:59]
	v_mfma_f32_16x16x128_f8f6f4 v[52:55], v[26:33], v[232:239], v[52:55]
	v_mfma_f32_16x16x128_f8f6f4 v[40:43], v[18:25], v[240:247], v[40:43]
	v_mfma_f32_16x16x128_f8f6f4 v[36:39], v[26:33], v[240:247], v[36:39]
	s_setprio 0
	s_barrier
	s_add_i32 s34, s34, 2
	s_add_u32 s8, s8, 0x100
	s_addc_u32 s9, s9, 0
	s_add_u32 s29, s29, 0x100
	s_addc_u32 s31, s31, 0
	s_cmp_gt_u32 s34, 29
	s_cbranch_scc0 .LBB0_200
	s_and_b64 vcc, exec, s[66:67]
	s_cbranch_vccz .LBB0_203
	s_barrier

.LBB0_1446:
	s_add_u32 s10, s26, s8
	s_addc_u32 s11, s27, s9
	s_add_u32 s10, s10, 0x55a00100
	s_addc_u32 s11, s11, 0
	s_add_u32 s29, s24, s8
	s_addc_u32 s30, s25, s9
	s_add_i32 s31, 0, 0x10000
	s_cmpk_eq_i32 s8, 0xf00
	s_cselect_b32 s13, s7, s11
	s_cselect_b32 s12, s6, s10
	v_add_u32_e32 v1, s31, v146
	s_cselect_b32 s11, s1, s30
	s_cselect_b32 s10, s0, s29
	s_add_i32 s29, 0, 0x14000
	ds_read_b128 v[148:151], v1
	ds_read_b128 v[152:155], v1 offset:1024
	ds_read_b128 v[156:159], v1 offset:2048
	ds_read_b128 v[160:163], v1 offset:3072
	v_add_u32_e32 v1, s29, v146
	ds_read_b128 v[172:175], v1
	ds_read_b128 v[176:179], v1 offset:1024
	ds_read_b128 v[180:183], v1 offset:2048
	ds_read_b128 v[184:187], v1 offset:3072
	v_lshl_add_u64 v[216:217], v[144:145], 0, s[8:9]
	s_add_i32 m0, s16, 0xc000
	ds_read_b128 v[188:191], v147
	ds_read_b128 v[192:195], v147 offset:1024
	ds_read_b128 v[196:199], v147 offset:2048
	ds_read_b128 v[200:203], v147 offset:3072
	ds_read_b128 v[204:207], v147 offset:4096
	ds_read_b128 v[208:211], v147 offset:5120
	ds_read_b128 v[212:215], v147 offset:6144
	ds_read_b128 v[232:235], v147 offset:7168
	global_load_lds_dwordx4 v[216:217], off
	v_lshl_add_u64 v[216:217], v[142:143], 0, s[8:9]
	s_add_i32 m0, s16, 0xe000
	s_nop 0
	global_load_lds_dwordx4 v[216:217], off
	s_waitcnt vmcnt(8)
	s_waitcnt lgkmcnt(0)
	s_barrier
	s_setprio 1
	s_waitcnt lgkmcnt(0)
	v_mfma_f32_16x16x32_bf16 v[128:131], v[148:151], v[188:191], v[128:131]
	v_mfma_f32_16x16x32_bf16 v[124:127], v[156:159], v[188:191], v[124:127]
	v_mfma_f32_16x16x32_bf16 v[116:119], v[148:151], v[196:199], v[116:119]
	v_mfma_f32_16x16x32_bf16 v[108:111], v[156:159], v[196:199], v[108:111]
	v_mfma_f32_16x16x32_bf16 v[100:103], v[148:151], v[204:207], v[100:103]
	v_mfma_f32_16x16x32_bf16 v[92:95], v[156:159], v[204:207], v[92:95]
	v_mfma_f32_16x16x32_bf16 v[84:87], v[148:151], v[212:215], v[84:87]
	v_mfma_f32_16x16x32_bf16 v[76:79], v[156:159], v[212:215], v[76:79]
	v_mfma_f32_16x16x32_bf16 v[128:131], v[152:155], v[192:195], v[128:131]
	v_mfma_f32_16x16x32_bf16 v[124:127], v[160:163], v[192:195], v[124:127]
	v_mfma_f32_16x16x32_bf16 v[116:119], v[152:155], v[200:203], v[116:119]
	v_mfma_f32_16x16x32_bf16 v[108:111], v[160:163], v[200:203], v[108:111]
	v_mfma_f32_16x16x32_bf16 v[100:103], v[152:155], v[208:211], v[100:103]
	v_mfma_f32_16x16x32_bf16 v[92:95], v[160:163], v[208:211], v[92:95]
	v_mfma_f32_16x16x32_bf16 v[84:87], v[152:155], v[232:235], v[84:87]
	v_mfma_f32_16x16x32_bf16 v[76:79], v[160:163], v[232:235], v[76:79]
	v_mfma_f32_16x16x32_bf16 v[120:123], v[172:175], v[188:191], v[120:123]
	v_mfma_f32_16x16x32_bf16 v[112:115], v[180:183], v[188:191], v[112:115]
	v_mfma_f32_16x16x32_bf16 v[104:107], v[172:175], v[196:199], v[104:107]
	v_mfma_f32_16x16x32_bf16 v[96:99], v[180:183], v[196:199], v[96:99]
	v_mfma_f32_16x16x32_bf16 v[88:91], v[172:175], v[204:207], v[88:91]
	v_mfma_f32_16x16x32_bf16 v[80:83], v[180:183], v[204:207], v[80:83]
	v_mfma_f32_16x16x32_bf16 v[72:75], v[172:175], v[212:215], v[72:75]
	v_mfma_f32_16x16x32_bf16 v[68:71], v[180:183], v[212:215], v[68:71]
	v_mfma_f32_16x16x32_bf16 v[120:123], v[176:179], v[192:195], v[120:123]
	v_mfma_f32_16x16x32_bf16 v[112:115], v[184:187], v[192:195], v[112:115]
	v_mfma_f32_16x16x32_bf16 v[104:107], v[176:179], v[200:203], v[104:107]
	v_mfma_f32_16x16x32_bf16 v[96:99], v[184:187], v[200:203], v[96:99]
	v_mfma_f32_16x16x32_bf16 v[88:91], v[176:179], v[208:211], v[88:91]
	v_mfma_f32_16x16x32_bf16 v[80:83], v[184:187], v[208:211], v[80:83]
	v_mfma_f32_16x16x32_bf16 v[72:75], v[176:179], v[232:235], v[72:75]
	v_mfma_f32_16x16x32_bf16 v[68:71], v[184:187], v[232:235], v[68:71]
	s_setprio 0
	s_barrier
	s_add_i32 s30, s31, s15
	v_lshl_add_u64 v[216:217], s[10:11], 0, v[134:135]
	s_mov_b32 m0, s30
	ds_read_b128 v[188:191], v147 offset:16384
	ds_read_b128 v[192:195], v147 offset:17408
	ds_read_b128 v[196:199], v147 offset:18432
	ds_read_b128 v[200:203], v147 offset:19456
	ds_read_b128 v[204:207], v147 offset:20480
	ds_read_b128 v[208:211], v147 offset:21504
	ds_read_b128 v[212:215], v147 offset:22528
	ds_read_b128 v[232:235], v147 offset:23552
	global_load_lds_dwordx4 v[216:217], off
	s_add_i32 m0, s30, 0x2000
	s_add_u32 s30, s10, 0x180000
	v_lshl_add_u64 v[220:221], s[10:11], 0, v[138:139]
	s_addc_u32 s31, s11, 0
	s_add_i32 s29, s29, s15
	global_load_lds_dwordx4 v[220:221], off
	v_lshl_add_u64 v[236:237], s[30:31], 0, v[134:135]
	s_mov_b32 m0, s29
	v_lshl_add_u64 v[238:239], s[12:13], 0, v[136:137]
	global_load_lds_dwordx4 v[236:237], off
	v_lshl_add_u64 v[236:237], s[30:31], 0, v[138:139]
	s_add_i32 m0, s29, 0x2000
	s_nop 0
	global_load_lds_dwordx4 v[236:237], off
	v_lshl_add_u64 v[236:237], s[12:13], 0, v[132:133]
	s_mov_b32 m0, s16
	s_nop 0
	global_load_lds_dwordx4 v[236:237], off
	s_mov_b32 m0, s17
	s_nop 0
	global_load_lds_dwordx4 v[238:239], off
	s_waitcnt vmcnt(8)
	s_waitcnt lgkmcnt(0)
	s_barrier
	s_setprio 1
	s_waitcnt lgkmcnt(0)
	v_mfma_f32_16x16x32_bf16 v[64:67], v[148:151], v[188:191], v[64:67]
	v_mfma_f32_16x16x32_bf16 v[60:63], v[156:159], v[188:191], v[60:63]
	v_mfma_f32_16x16x32_bf16 v[52:55], v[148:151], v[196:199], v[52:55]
	v_mfma_f32_16x16x32_bf16 v[44:47], v[156:159], v[196:199], v[44:47]
	v_mfma_f32_16x16x32_bf16 v[36:39], v[148:151], v[204:207], v[36:39]
	v_mfma_f32_16x16x32_bf16 v[26:29], v[156:159], v[204:207], v[26:29]
	v_mfma_f32_16x16x32_bf16 v[18:21], v[148:151], v[212:215], v[18:21]
	v_mfma_f32_16x16x32_bf16 v[10:13], v[156:159], v[212:215], v[10:13]
	v_mfma_f32_16x16x32_bf16 v[64:67], v[152:155], v[192:195], v[64:67]
	v_mfma_f32_16x16x32_bf16 v[60:63], v[160:163], v[192:195], v[60:63]
	v_mfma_f32_16x16x32_bf16 v[52:55], v[152:155], v[200:203], v[52:55]
	v_mfma_f32_16x16x32_bf16 v[44:47], v[160:163], v[200:203], v[44:47]
	v_mfma_f32_16x16x32_bf16 v[36:39], v[152:155], v[208:211], v[36:39]
	v_mfma_f32_16x16x32_bf16 v[26:29], v[160:163], v[208:211], v[26:29]
	v_mfma_f32_16x16x32_bf16 v[18:21], v[152:155], v[232:235], v[18:21]
	v_mfma_f32_16x16x32_bf16 v[10:13], v[160:163], v[232:235], v[10:13]
	v_mfma_f32_16x16x32_bf16 v[56:59], v[172:175], v[188:191], v[56:59]
	v_mfma_f32_16x16x32_bf16 v[48:51], v[180:183], v[188:191], v[48:51]
	v_mfma_f32_16x16x32_bf16 v[40:43], v[172:175], v[196:199], v[40:43]
	v_mfma_f32_16x16x32_bf16 v[30:33], v[180:183], v[196:199], v[30:33]
	v_mfma_f32_16x16x32_bf16 v[22:25], v[172:175], v[204:207], v[22:25]
	v_mfma_f32_16x16x32_bf16 v[14:17], v[180:183], v[204:207], v[14:17]
	v_mfma_f32_16x16x32_bf16 v[6:9], v[172:175], v[212:215], v[6:9]
	v_mfma_f32_16x16x32_bf16 v[2:5], v[180:183], v[212:215], v[2:5]
	v_mfma_f32_16x16x32_bf16 v[56:59], v[176:179], v[192:195], v[56:59]
	v_mfma_f32_16x16x32_bf16 v[48:51], v[184:187], v[192:195], v[48:51]
	v_mfma_f32_16x16x32_bf16 v[40:43], v[176:179], v[200:203], v[40:43]
	v_mfma_f32_16x16x32_bf16 v[30:33], v[184:187], v[200:203], v[30:33]
	v_mfma_f32_16x16x32_bf16 v[22:25], v[176:179], v[208:211], v[22:25]
	v_mfma_f32_16x16x32_bf16 v[14:17], v[184:187], v[208:211], v[14:17]
	v_mfma_f32_16x16x32_bf16 v[6:9], v[176:179], v[232:235], v[6:9]
	v_mfma_f32_16x16x32_bf16 v[2:5], v[184:187], v[232:235], v[2:5]
	s_setprio 0
	s_barrier
	s_add_i32 s29, 0, 0x18000
	v_add_u32_e32 v1, s29, v146
	s_add_i32 s30, 0, 0x1c000
	ds_read_b128 v[148:151], v1
	ds_read_b128 v[152:155], v1 offset:1024
	ds_read_b128 v[156:159], v1 offset:2048
	ds_read_b128 v[160:163], v1 offset:3072
	v_add_u32_e32 v1, s30, v146
	ds_read_b128 v[172:175], v1
	ds_read_b128 v[176:179], v1 offset:1024
	ds_read_b128 v[180:183], v1 offset:2048
	ds_read_b128 v[184:187], v1 offset:3072
	s_add_u32 s12, s12, 0x180000
	s_addc_u32 s13, s13, 0
	s_mov_b32 m0, s18
	v_lshl_add_u64 v[240:241], s[12:13], 0, v[132:133]
	ds_read_b128 v[188:191], v147 offset:32768
	ds_read_b128 v[192:195], v147 offset:33792
	ds_read_b128 v[196:199], v147 offset:34816
	ds_read_b128 v[200:203], v147 offset:35840
	ds_read_b128 v[204:207], v147 offset:36864
	ds_read_b128 v[208:211], v147 offset:37888
	ds_read_b128 v[212:215], v147 offset:38912
	ds_read_b128 v[232:235], v147 offset:39936
	global_load_lds_dwordx4 v[240:241], off
	v_lshl_add_u64 v[240:241], s[12:13], 0, v[136:137]
	s_mov_b32 m0, s19
	s_nop 0
	global_load_lds_dwordx4 v[240:241], off
	s_waitcnt vmcnt(8)
	s_waitcnt lgkmcnt(0)
	s_barrier
	s_setprio 1
	s_waitcnt lgkmcnt(0)
	v_mfma_f32_16x16x32_bf16 v[128:131], v[148:151], v[188:191], v[128:131]
	v_mfma_f32_16x16x32_bf16 v[124:127], v[156:159], v[188:191], v[124:127]
	v_mfma_f32_16x16x32_bf16 v[116:119], v[148:151], v[196:199], v[116:119]
	v_mfma_f32_16x16x32_bf16 v[108:111], v[156:159], v[196:199], v[108:111]
	v_mfma_f32_16x16x32_bf16 v[100:103], v[148:151], v[204:207], v[100:103]
	v_mfma_f32_16x16x32_bf16 v[92:95], v[156:159], v[204:207], v[92:95]
	v_mfma_f32_16x16x32_bf16 v[84:87], v[148:151], v[212:215], v[84:87]
	v_mfma_f32_16x16x32_bf16 v[76:79], v[156:159], v[212:215], v[76:79]
	v_mfma_f32_16x16x32_bf16 v[128:131], v[152:155], v[192:195], v[128:131]
	v_mfma_f32_16x16x32_bf16 v[124:127], v[160:163], v[192:195], v[124:127]
	v_mfma_f32_16x16x32_bf16 v[116:119], v[152:155], v[200:203], v[116:119]
	v_mfma_f32_16x16x32_bf16 v[108:111], v[160:163], v[200:203], v[108:111]
	v_mfma_f32_16x16x32_bf16 v[100:103], v[152:155], v[208:211], v[100:103]
	v_mfma_f32_16x16x32_bf16 v[92:95], v[160:163], v[208:211], v[92:95]
	v_mfma_f32_16x16x32_bf16 v[84:87], v[152:155], v[232:235], v[84:87]
	v_mfma_f32_16x16x32_bf16 v[76:79], v[160:163], v[232:235], v[76:79]
	v_mfma_f32_16x16x32_bf16 v[120:123], v[172:175], v[188:191], v[120:123]
	v_mfma_f32_16x16x32_bf16 v[112:115], v[180:183], v[188:191], v[112:115]
	v_mfma_f32_16x16x32_bf16 v[104:107], v[172:175], v[196:199], v[104:107]
	v_mfma_f32_16x16x32_bf16 v[96:99], v[180:183], v[196:199], v[96:99]
	v_mfma_f32_16x16x32_bf16 v[88:91], v[172:175], v[204:207], v[88:91]
	v_mfma_f32_16x16x32_bf16 v[80:83], v[180:183], v[204:207], v[80:83]
	v_mfma_f32_16x16x32_bf16 v[72:75], v[172:175], v[212:215], v[72:75]
	v_mfma_f32_16x16x32_bf16 v[68:71], v[180:183], v[212:215], v[68:71]
	v_mfma_f32_16x16x32_bf16 v[120:123], v[176:179], v[192:195], v[120:123]
	v_mfma_f32_16x16x32_bf16 v[112:115], v[184:187], v[192:195], v[112:115]
	v_mfma_f32_16x16x32_bf16 v[104:107], v[176:179], v[200:203], v[104:107]
	v_mfma_f32_16x16x32_bf16 v[96:99], v[184:187], v[200:203], v[96:99]
	v_mfma_f32_16x16x32_bf16 v[88:91], v[176:179], v[208:211], v[88:91]
	v_mfma_f32_16x16x32_bf16 v[80:83], v[184:187], v[208:211], v[80:83]
	v_mfma_f32_16x16x32_bf16 v[72:75], v[176:179], v[232:235], v[72:75]
	v_mfma_f32_16x16x32_bf16 v[68:71], v[184:187], v[232:235], v[68:71]
	s_setprio 0
	s_barrier
	s_add_i32 s12, s29, s15
	v_lshl_add_u64 v[216:217], v[216:217], 0, s[2:3]
	s_mov_b32 m0, s12
	ds_read_b128 v[188:191], v147 offset:49152
	ds_read_b128 v[192:195], v147 offset:50176
	ds_read_b128 v[196:199], v147 offset:51200
	ds_read_b128 v[200:203], v147 offset:52224
	ds_read_b128 v[204:207], v147 offset:53248
	ds_read_b128 v[208:211], v147 offset:54272
	ds_read_b128 v[212:215], v147 offset:55296
	ds_read_b128 v[232:235], v147 offset:56320
	global_load_lds_dwordx4 v[216:217], off
	s_add_i32 m0, s12, 0x2000
	s_add_u32 s10, s10, 0x180080
	v_lshl_add_u64 v[216:217], v[220:221], 0, s[2:3]
	s_addc_u32 s11, s11, 0
	s_add_i32 s12, s30, s15
	global_load_lds_dwordx4 v[216:217], off
	v_lshl_add_u64 v[216:217], s[10:11], 0, v[134:135]
	s_mov_b32 m0, s12
	s_nop 0
	global_load_lds_dwordx4 v[216:217], off
	v_lshl_add_u64 v[216:217], s[10:11], 0, v[138:139]
	s_add_i32 m0, s12, 0x2000
	s_nop 0
	global_load_lds_dwordx4 v[216:217], off
	v_lshl_add_u64 v[216:217], v[236:237], 0, s[2:3]
	s_mov_b32 m0, s22
	s_nop 0
	global_load_lds_dwordx4 v[216:217], off
	v_lshl_add_u64 v[216:217], v[238:239], 0, s[2:3]
	s_mov_b32 m0, s23
	s_nop 0
	global_load_lds_dwordx4 v[216:217], off
	s_waitcnt vmcnt(8)
	s_waitcnt lgkmcnt(0)
	s_barrier
	s_setprio 1
	s_waitcnt lgkmcnt(0)
	v_mfma_f32_16x16x32_bf16 v[64:67], v[148:151], v[188:191], v[64:67]
	v_mfma_f32_16x16x32_bf16 v[60:63], v[156:159], v[188:191], v[60:63]
	v_mfma_f32_16x16x32_bf16 v[52:55], v[148:151], v[196:199], v[52:55]
	v_mfma_f32_16x16x32_bf16 v[44:47], v[156:159], v[196:199], v[44:47]
	v_mfma_f32_16x16x32_bf16 v[36:39], v[148:151], v[204:207], v[36:39]
	v_mfma_f32_16x16x32_bf16 v[26:29], v[156:159], v[204:207], v[26:29]
	v_mfma_f32_16x16x32_bf16 v[18:21], v[148:151], v[212:215], v[18:21]
	v_mfma_f32_16x16x32_bf16 v[10:13], v[156:159], v[212:215], v[10:13]
	v_mfma_f32_16x16x32_bf16 v[64:67], v[152:155], v[192:195], v[64:67]
	v_mfma_f32_16x16x32_bf16 v[60:63], v[160:163], v[192:195], v[60:63]
	v_mfma_f32_16x16x32_bf16 v[52:55], v[152:155], v[200:203], v[52:55]
	v_mfma_f32_16x16x32_bf16 v[44:47], v[160:163], v[200:203], v[44:47]
	v_mfma_f32_16x16x32_bf16 v[36:39], v[152:155], v[208:211], v[36:39]
	v_mfma_f32_16x16x32_bf16 v[26:29], v[160:163], v[208:211], v[26:29]
	v_mfma_f32_16x16x32_bf16 v[18:21], v[152:155], v[232:235], v[18:21]
	v_mfma_f32_16x16x32_bf16 v[10:13], v[160:163], v[232:235], v[10:13]
	v_mfma_f32_16x16x32_bf16 v[56:59], v[172:175], v[188:191], v[56:59]
	v_mfma_f32_16x16x32_bf16 v[48:51], v[180:183], v[188:191], v[48:51]
	v_mfma_f32_16x16x32_bf16 v[40:43], v[172:175], v[196:199], v[40:43]
	v_mfma_f32_16x16x32_bf16 v[30:33], v[180:183], v[196:199], v[30:33]
	v_mfma_f32_16x16x32_bf16 v[22:25], v[172:175], v[204:207], v[22:25]
	v_mfma_f32_16x16x32_bf16 v[14:17], v[180:183], v[204:207], v[14:17]
	v_mfma_f32_16x16x32_bf16 v[6:9], v[172:175], v[212:215], v[6:9]
	v_mfma_f32_16x16x32_bf16 v[2:5], v[180:183], v[212:215], v[2:5]
	v_mfma_f32_16x16x32_bf16 v[56:59], v[176:179], v[192:195], v[56:59]
	v_mfma_f32_16x16x32_bf16 v[48:51], v[184:187], v[192:195], v[48:51]
	v_mfma_f32_16x16x32_bf16 v[40:43], v[176:179], v[200:203], v[40:43]
	v_mfma_f32_16x16x32_bf16 v[30:33], v[184:187], v[200:203], v[30:33]
	v_mfma_f32_16x16x32_bf16 v[22:25], v[176:179], v[208:211], v[22:25]
	v_mfma_f32_16x16x32_bf16 v[14:17], v[184:187], v[208:211], v[14:17]
	v_mfma_f32_16x16x32_bf16 v[6:9], v[176:179], v[232:235], v[6:9]
	v_mfma_f32_16x16x32_bf16 v[2:5], v[184:187], v[232:235], v[2:5]
	s_setprio 0
	s_barrier
	s_add_i32 s28, s28, 2
	s_add_u32 s8, s8, 0x100
	s_addc_u32 s9, s9, 0
	s_cmp_gt_u32 s28, 29
	s_cbranch_scc0 .LBB0_1446
	s_waitcnt vmcnt(0)
	s_cmpk_lt_u32 s14, 0x100
	s_cbranch_scc0 .LBB0_1449
	s_barrier

.LBB0_1491:
	s_add_u32 s8, s24, s6
	s_addc_u32 s9, s25, s7
	s_add_u32 s8, s8, 0x6a700100
	s_addc_u32 s9, s9, 0
	s_add_u32 s27, s22, s6
	s_addc_u32 s28, s23, s7
	s_add_i32 s29, 0, 0x10000
	s_cmpk_eq_i32 s6, 0x700
	s_cselect_b32 s11, s5, s9
	s_cselect_b32 s10, s4, s8
	v_add_u32_e32 v1, s29, v145
	s_cselect_b32 s9, s1, s28
	s_cselect_b32 s8, s0, s27
	s_add_i32 s27, 0, 0x14000
	ds_read_b128 v[148:151], v1
	ds_read_b128 v[152:155], v1 offset:1024
	ds_read_b128 v[156:159], v1 offset:2048
	ds_read_b128 v[160:163], v1 offset:3072
	v_add_u32_e32 v1, s27, v145
	ds_read_b128 v[172:175], v1
	ds_read_b128 v[176:179], v1 offset:1024
	ds_read_b128 v[180:183], v1 offset:2048
	ds_read_b128 v[184:187], v1 offset:3072
	v_lshl_add_u64 v[216:217], v[142:143], 0, s[6:7]
	s_add_i32 m0, s14, 0xc000
	ds_read_b128 v[188:191], v146
	ds_read_b128 v[192:195], v146 offset:1024
	ds_read_b128 v[196:199], v146 offset:2048
	ds_read_b128 v[200:203], v146 offset:3072
	ds_read_b128 v[204:207], v146 offset:4096
	ds_read_b128 v[208:211], v146 offset:5120
	ds_read_b128 v[212:215], v146 offset:6144
	ds_read_b128 v[232:235], v146 offset:7168
	global_load_lds_dwordx4 v[216:217], off
	v_lshl_add_u64 v[216:217], v[140:141], 0, s[6:7]
	s_add_i32 m0, s14, 0xe000
	s_nop 0
	global_load_lds_dwordx4 v[216:217], off
	s_waitcnt vmcnt(8)
	s_waitcnt lgkmcnt(0)
	s_barrier
	s_setprio 1
	s_waitcnt lgkmcnt(0)
	v_mfma_f32_16x16x32_bf16 v[128:131], v[148:151], v[188:191], v[128:131]
	v_mfma_f32_16x16x32_bf16 v[124:127], v[156:159], v[188:191], v[124:127]
	v_mfma_f32_16x16x32_bf16 v[120:123], v[148:151], v[196:199], v[120:123]
	v_mfma_f32_16x16x32_bf16 v[116:119], v[156:159], v[196:199], v[116:119]
	v_mfma_f32_16x16x32_bf16 v[108:111], v[148:151], v[204:207], v[108:111]
	v_mfma_f32_16x16x32_bf16 v[100:103], v[156:159], v[204:207], v[100:103]
	v_mfma_f32_16x16x32_bf16 v[92:95], v[148:151], v[212:215], v[92:95]
	v_mfma_f32_16x16x32_bf16 v[84:87], v[156:159], v[212:215], v[84:87]
	v_mfma_f32_16x16x32_bf16 v[128:131], v[152:155], v[192:195], v[128:131]
	v_mfma_f32_16x16x32_bf16 v[124:127], v[160:163], v[192:195], v[124:127]
	v_mfma_f32_16x16x32_bf16 v[120:123], v[152:155], v[200:203], v[120:123]
	v_mfma_f32_16x16x32_bf16 v[116:119], v[160:163], v[200:203], v[116:119]
	v_mfma_f32_16x16x32_bf16 v[108:111], v[152:155], v[208:211], v[108:111]
	v_mfma_f32_16x16x32_bf16 v[100:103], v[160:163], v[208:211], v[100:103]
	v_mfma_f32_16x16x32_bf16 v[92:95], v[152:155], v[232:235], v[92:95]
	v_mfma_f32_16x16x32_bf16 v[84:87], v[160:163], v[232:235], v[84:87]
	v_mfma_f32_16x16x32_bf16 v[112:115], v[172:175], v[188:191], v[112:115]
	v_mfma_f32_16x16x32_bf16 v[104:107], v[180:183], v[188:191], v[104:107]
	v_mfma_f32_16x16x32_bf16 v[96:99], v[172:175], v[196:199], v[96:99]
	v_mfma_f32_16x16x32_bf16 v[88:91], v[180:183], v[196:199], v[88:91]
	v_mfma_f32_16x16x32_bf16 v[80:83], v[172:175], v[204:207], v[80:83]
	v_mfma_f32_16x16x32_bf16 v[76:79], v[180:183], v[204:207], v[76:79]
	v_mfma_f32_16x16x32_bf16 v[72:75], v[172:175], v[212:215], v[72:75]
	v_mfma_f32_16x16x32_bf16 v[68:71], v[180:183], v[212:215], v[68:71]
	v_mfma_f32_16x16x32_bf16 v[112:115], v[176:179], v[192:195], v[112:115]
	v_mfma_f32_16x16x32_bf16 v[104:107], v[184:187], v[192:195], v[104:107]
	v_mfma_f32_16x16x32_bf16 v[96:99], v[176:179], v[200:203], v[96:99]
	v_mfma_f32_16x16x32_bf16 v[88:91], v[184:187], v[200:203], v[88:91]
	v_mfma_f32_16x16x32_bf16 v[80:83], v[176:179], v[208:211], v[80:83]
	v_mfma_f32_16x16x32_bf16 v[76:79], v[184:187], v[208:211], v[76:79]
	v_mfma_f32_16x16x32_bf16 v[72:75], v[176:179], v[232:235], v[72:75]
	v_mfma_f32_16x16x32_bf16 v[68:71], v[184:187], v[232:235], v[68:71]
	s_setprio 0
	s_barrier
	s_add_i32 s28, s29, s13
	v_lshl_add_u64 v[216:217], s[8:9], 0, v[134:135]
	s_mov_b32 m0, s28
	ds_read_b128 v[188:191], v146 offset:16384
	ds_read_b128 v[192:195], v146 offset:17408
	ds_read_b128 v[196:199], v146 offset:18432
	ds_read_b128 v[200:203], v146 offset:19456
	ds_read_b128 v[204:207], v146 offset:20480
	ds_read_b128 v[208:211], v146 offset:21504
	ds_read_b128 v[212:215], v146 offset:22528
	ds_read_b128 v[232:235], v146 offset:23552
	global_load_lds_dwordx4 v[216:217], off
	s_add_i32 m0, s28, 0x2000
	s_add_u32 s28, s8, 0x100000
	v_lshl_add_u64 v[220:221], s[8:9], 0, v[138:139]
	s_addc_u32 s29, s9, 0
	s_add_i32 s27, s27, s13
	global_load_lds_dwordx4 v[220:221], off
	v_lshl_add_u64 v[236:237], s[28:29], 0, v[134:135]
	s_mov_b32 m0, s27
	v_lshl_add_u64 v[238:239], s[10:11], 0, v[136:137]
	global_load_lds_dwordx4 v[236:237], off
	v_lshl_add_u64 v[236:237], s[28:29], 0, v[138:139]
	s_add_i32 m0, s27, 0x2000
	s_nop 0
	global_load_lds_dwordx4 v[236:237], off
	v_lshl_add_u64 v[236:237], s[10:11], 0, v[132:133]
	s_mov_b32 m0, s14
	s_nop 0
	global_load_lds_dwordx4 v[236:237], off
	s_mov_b32 m0, s15
	s_nop 0
	global_load_lds_dwordx4 v[238:239], off
	s_waitcnt vmcnt(8)
	s_waitcnt lgkmcnt(0)
	s_barrier
	s_setprio 1
	s_waitcnt lgkmcnt(0)
	v_mfma_f32_16x16x32_bf16 v[64:67], v[148:151], v[188:191], v[64:67]
	v_mfma_f32_16x16x32_bf16 v[60:63], v[156:159], v[188:191], v[60:63]
	v_mfma_f32_16x16x32_bf16 v[56:59], v[148:151], v[196:199], v[56:59]
	v_mfma_f32_16x16x32_bf16 v[52:55], v[156:159], v[196:199], v[52:55]
	v_mfma_f32_16x16x32_bf16 v[40:43], v[148:151], v[204:207], v[40:43]
	v_mfma_f32_16x16x32_bf16 v[36:39], v[156:159], v[204:207], v[36:39]
	v_mfma_f32_16x16x32_bf16 v[22:25], v[148:151], v[212:215], v[22:25]
	v_mfma_f32_16x16x32_bf16 v[18:21], v[156:159], v[212:215], v[18:21]
	v_mfma_f32_16x16x32_bf16 v[64:67], v[152:155], v[192:195], v[64:67]
	v_mfma_f32_16x16x32_bf16 v[60:63], v[160:163], v[192:195], v[60:63]
	v_mfma_f32_16x16x32_bf16 v[56:59], v[152:155], v[200:203], v[56:59]
	v_mfma_f32_16x16x32_bf16 v[52:55], v[160:163], v[200:203], v[52:55]
	v_mfma_f32_16x16x32_bf16 v[40:43], v[152:155], v[208:211], v[40:43]
	v_mfma_f32_16x16x32_bf16 v[36:39], v[160:163], v[208:211], v[36:39]
	v_mfma_f32_16x16x32_bf16 v[22:25], v[152:155], v[232:235], v[22:25]
	v_mfma_f32_16x16x32_bf16 v[18:21], v[160:163], v[232:235], v[18:21]
	v_mfma_f32_16x16x32_bf16 v[48:51], v[172:175], v[188:191], v[48:51]
	v_mfma_f32_16x16x32_bf16 v[44:47], v[180:183], v[188:191], v[44:47]
	v_mfma_f32_16x16x32_bf16 v[30:33], v[172:175], v[196:199], v[30:33]
	v_mfma_f32_16x16x32_bf16 v[26:29], v[180:183], v[196:199], v[26:29]
	v_mfma_f32_16x16x32_bf16 v[14:17], v[172:175], v[204:207], v[14:17]
	v_mfma_f32_16x16x32_bf16 v[10:13], v[180:183], v[204:207], v[10:13]
	v_mfma_f32_16x16x32_bf16 v[6:9], v[172:175], v[212:215], v[6:9]
	v_mfma_f32_16x16x32_bf16 v[2:5], v[180:183], v[212:215], v[2:5]
	v_mfma_f32_16x16x32_bf16 v[48:51], v[176:179], v[192:195], v[48:51]
	v_mfma_f32_16x16x32_bf16 v[44:47], v[184:187], v[192:195], v[44:47]
	v_mfma_f32_16x16x32_bf16 v[30:33], v[176:179], v[200:203], v[30:33]
	v_mfma_f32_16x16x32_bf16 v[26:29], v[184:187], v[200:203], v[26:29]
	v_mfma_f32_16x16x32_bf16 v[14:17], v[176:179], v[208:211], v[14:17]
	v_mfma_f32_16x16x32_bf16 v[10:13], v[184:187], v[208:211], v[10:13]
	v_mfma_f32_16x16x32_bf16 v[6:9], v[176:179], v[232:235], v[6:9]
	v_mfma_f32_16x16x32_bf16 v[2:5], v[184:187], v[232:235], v[2:5]
	s_setprio 0
	s_barrier
	s_add_i32 s27, 0, 0x18000
	v_add_u32_e32 v1, s27, v145
	s_add_i32 s28, 0, 0x1c000
	ds_read_b128 v[148:151], v1
	ds_read_b128 v[152:155], v1 offset:1024
	ds_read_b128 v[156:159], v1 offset:2048
	ds_read_b128 v[160:163], v1 offset:3072
	v_add_u32_e32 v1, s28, v145
	ds_read_b128 v[172:175], v1
	ds_read_b128 v[176:179], v1 offset:1024
	ds_read_b128 v[180:183], v1 offset:2048
	ds_read_b128 v[184:187], v1 offset:3072
	s_add_u32 s10, s10, 0x100000
	s_addc_u32 s11, s11, 0
	s_mov_b32 m0, s16
	v_lshl_add_u64 v[240:241], s[10:11], 0, v[132:133]
	ds_read_b128 v[188:191], v146 offset:32768
	ds_read_b128 v[192:195], v146 offset:33792
	ds_read_b128 v[196:199], v146 offset:34816
	ds_read_b128 v[200:203], v146 offset:35840
	ds_read_b128 v[204:207], v146 offset:36864
	ds_read_b128 v[208:211], v146 offset:37888
	ds_read_b128 v[212:215], v146 offset:38912
	ds_read_b128 v[232:235], v146 offset:39936
	global_load_lds_dwordx4 v[240:241], off
	v_lshl_add_u64 v[240:241], s[10:11], 0, v[136:137]
	s_mov_b32 m0, s17
	s_nop 0
	global_load_lds_dwordx4 v[240:241], off
	s_waitcnt vmcnt(8)
	s_waitcnt lgkmcnt(0)
	s_barrier
	s_setprio 1
	s_waitcnt lgkmcnt(0)
	v_mfma_f32_16x16x32_bf16 v[128:131], v[148:151], v[188:191], v[128:131]
	v_mfma_f32_16x16x32_bf16 v[124:127], v[156:159], v[188:191], v[124:127]
	v_mfma_f32_16x16x32_bf16 v[120:123], v[148:151], v[196:199], v[120:123]
	v_mfma_f32_16x16x32_bf16 v[116:119], v[156:159], v[196:199], v[116:119]
	v_mfma_f32_16x16x32_bf16 v[108:111], v[148:151], v[204:207], v[108:111]
	v_mfma_f32_16x16x32_bf16 v[100:103], v[156:159], v[204:207], v[100:103]
	v_mfma_f32_16x16x32_bf16 v[92:95], v[148:151], v[212:215], v[92:95]
	v_mfma_f32_16x16x32_bf16 v[84:87], v[156:159], v[212:215], v[84:87]
	v_mfma_f32_16x16x32_bf16 v[128:131], v[152:155], v[192:195], v[128:131]
	v_mfma_f32_16x16x32_bf16 v[124:127], v[160:163], v[192:195], v[124:127]
	v_mfma_f32_16x16x32_bf16 v[120:123], v[152:155], v[200:203], v[120:123]
	v_mfma_f32_16x16x32_bf16 v[116:119], v[160:163], v[200:203], v[116:119]
	v_mfma_f32_16x16x32_bf16 v[108:111], v[152:155], v[208:211], v[108:111]
	v_mfma_f32_16x16x32_bf16 v[100:103], v[160:163], v[208:211], v[100:103]
	v_mfma_f32_16x16x32_bf16 v[92:95], v[152:155], v[232:235], v[92:95]
	v_mfma_f32_16x16x32_bf16 v[84:87], v[160:163], v[232:235], v[84:87]
	v_mfma_f32_16x16x32_bf16 v[112:115], v[172:175], v[188:191], v[112:115]
	v_mfma_f32_16x16x32_bf16 v[104:107], v[180:183], v[188:191], v[104:107]
	v_mfma_f32_16x16x32_bf16 v[96:99], v[172:175], v[196:199], v[96:99]
	v_mfma_f32_16x16x32_bf16 v[88:91], v[180:183], v[196:199], v[88:91]
	v_mfma_f32_16x16x32_bf16 v[80:83], v[172:175], v[204:207], v[80:83]
	v_mfma_f32_16x16x32_bf16 v[76:79], v[180:183], v[204:207], v[76:79]
	v_mfma_f32_16x16x32_bf16 v[72:75], v[172:175], v[212:215], v[72:75]
	v_mfma_f32_16x16x32_bf16 v[68:71], v[180:183], v[212:215], v[68:71]
	v_mfma_f32_16x16x32_bf16 v[112:115], v[176:179], v[192:195], v[112:115]
	v_mfma_f32_16x16x32_bf16 v[104:107], v[184:187], v[192:195], v[104:107]
	v_mfma_f32_16x16x32_bf16 v[96:99], v[176:179], v[200:203], v[96:99]
	v_mfma_f32_16x16x32_bf16 v[88:91], v[184:187], v[200:203], v[88:91]
	v_mfma_f32_16x16x32_bf16 v[80:83], v[176:179], v[208:211], v[80:83]
	v_mfma_f32_16x16x32_bf16 v[76:79], v[184:187], v[208:211], v[76:79]
	v_mfma_f32_16x16x32_bf16 v[72:75], v[176:179], v[232:235], v[72:75]
	v_mfma_f32_16x16x32_bf16 v[68:71], v[184:187], v[232:235], v[68:71]
	s_setprio 0
	s_barrier
	s_add_i32 s10, s27, s13
	v_lshl_add_u64 v[216:217], v[216:217], 0, s[2:3]
	s_mov_b32 m0, s10
	ds_read_b128 v[188:191], v146 offset:49152
	ds_read_b128 v[192:195], v146 offset:50176
	ds_read_b128 v[196:199], v146 offset:51200
	ds_read_b128 v[200:203], v146 offset:52224
	ds_read_b128 v[204:207], v146 offset:53248
	ds_read_b128 v[208:211], v146 offset:54272
	ds_read_b128 v[212:215], v146 offset:55296
	ds_read_b128 v[232:235], v146 offset:56320
	global_load_lds_dwordx4 v[216:217], off
	s_add_i32 m0, s10, 0x2000
	s_add_u32 s8, s8, 0x100080
	v_lshl_add_u64 v[216:217], v[220:221], 0, s[2:3]
	s_addc_u32 s9, s9, 0
	s_add_i32 s10, s28, s13
	global_load_lds_dwordx4 v[216:217], off
	v_lshl_add_u64 v[216:217], s[8:9], 0, v[134:135]
	s_mov_b32 m0, s10
	s_nop 0
	global_load_lds_dwordx4 v[216:217], off
	v_lshl_add_u64 v[216:217], s[8:9], 0, v[138:139]
	s_add_i32 m0, s10, 0x2000
	s_nop 0
	global_load_lds_dwordx4 v[216:217], off
	v_lshl_add_u64 v[216:217], v[236:237], 0, s[2:3]
	s_mov_b32 m0, s20
	s_nop 0
	global_load_lds_dwordx4 v[216:217], off
	v_lshl_add_u64 v[216:217], v[238:239], 0, s[2:3]
	s_mov_b32 m0, s21
	s_nop 0
	global_load_lds_dwordx4 v[216:217], off
	s_waitcnt vmcnt(8)
	s_waitcnt lgkmcnt(0)
	s_barrier
	s_setprio 1
	s_waitcnt lgkmcnt(0)
	v_mfma_f32_16x16x32_bf16 v[64:67], v[148:151], v[188:191], v[64:67]
	v_mfma_f32_16x16x32_bf16 v[60:63], v[156:159], v[188:191], v[60:63]
	v_mfma_f32_16x16x32_bf16 v[56:59], v[148:151], v[196:199], v[56:59]
	v_mfma_f32_16x16x32_bf16 v[52:55], v[156:159], v[196:199], v[52:55]
	v_mfma_f32_16x16x32_bf16 v[40:43], v[148:151], v[204:207], v[40:43]
	v_mfma_f32_16x16x32_bf16 v[36:39], v[156:159], v[204:207], v[36:39]
	v_mfma_f32_16x16x32_bf16 v[22:25], v[148:151], v[212:215], v[22:25]
	v_mfma_f32_16x16x32_bf16 v[18:21], v[156:159], v[212:215], v[18:21]
	v_mfma_f32_16x16x32_bf16 v[64:67], v[152:155], v[192:195], v[64:67]
	v_mfma_f32_16x16x32_bf16 v[60:63], v[160:163], v[192:195], v[60:63]
	v_mfma_f32_16x16x32_bf16 v[56:59], v[152:155], v[200:203], v[56:59]
	v_mfma_f32_16x16x32_bf16 v[52:55], v[160:163], v[200:203], v[52:55]
	v_mfma_f32_16x16x32_bf16 v[40:43], v[152:155], v[208:211], v[40:43]
	v_mfma_f32_16x16x32_bf16 v[36:39], v[160:163], v[208:211], v[36:39]
	v_mfma_f32_16x16x32_bf16 v[22:25], v[152:155], v[232:235], v[22:25]
	v_mfma_f32_16x16x32_bf16 v[18:21], v[160:163], v[232:235], v[18:21]
	v_mfma_f32_16x16x32_bf16 v[48:51], v[172:175], v[188:191], v[48:51]
	v_mfma_f32_16x16x32_bf16 v[44:47], v[180:183], v[188:191], v[44:47]
	v_mfma_f32_16x16x32_bf16 v[30:33], v[172:175], v[196:199], v[30:33]
	v_mfma_f32_16x16x32_bf16 v[26:29], v[180:183], v[196:199], v[26:29]
	v_mfma_f32_16x16x32_bf16 v[14:17], v[172:175], v[204:207], v[14:17]
	v_mfma_f32_16x16x32_bf16 v[10:13], v[180:183], v[204:207], v[10:13]
	v_mfma_f32_16x16x32_bf16 v[6:9], v[172:175], v[212:215], v[6:9]
	v_mfma_f32_16x16x32_bf16 v[2:5], v[180:183], v[212:215], v[2:5]
	v_mfma_f32_16x16x32_bf16 v[48:51], v[176:179], v[192:195], v[48:51]
	v_mfma_f32_16x16x32_bf16 v[44:47], v[184:187], v[192:195], v[44:47]
	v_mfma_f32_16x16x32_bf16 v[30:33], v[176:179], v[200:203], v[30:33]
	v_mfma_f32_16x16x32_bf16 v[26:29], v[184:187], v[200:203], v[26:29]
	v_mfma_f32_16x16x32_bf16 v[14:17], v[176:179], v[208:211], v[14:17]
	v_mfma_f32_16x16x32_bf16 v[10:13], v[184:187], v[208:211], v[10:13]
	v_mfma_f32_16x16x32_bf16 v[6:9], v[176:179], v[232:235], v[6:9]
	v_mfma_f32_16x16x32_bf16 v[2:5], v[184:187], v[232:235], v[2:5]
	s_setprio 0
	s_barrier
	s_add_i32 s26, s26, 2
	s_add_u32 s6, s6, 0x100
	s_addc_u32 s7, s7, 0
	s_cmp_gt_u32 s26, 13
	s_cbranch_scc0 .LBB0_1491
	s_waitcnt vmcnt(0)
	s_cmpk_lt_u32 s12, 0x100
	s_cbranch_scc0 .LBB0_1494
	s_barrier

.LBB0_1624:
	s_add_u32 s20, s18, 0x100
	s_addc_u32 s21, s19, 0
	s_add_i32 s50, 0, 0x10000
	s_cmp_eq_u32 s41, 28
	s_cselect_b32 s25, s15, s21
	s_cselect_b32 s24, s14, s20
	v_add_u32_e32 v1, s50, v184
	s_cselect_b32 s23, s17, s40
	s_cselect_b32 s22, s16, s13
	s_add_i32 s51, 0, 0x14000
	s_waitcnt lgkmcnt(0)
	ds_read_b128 v[134:137], v1
	ds_read_b128 v[138:141], v1 offset:1024
	ds_read_b128 v[142:145], v1 offset:2048
	ds_read_b128 v[146:149], v1 offset:3072
	v_add_u32_e32 v1, s51, v184
	ds_read_b128 v[150:153], v1
	ds_read_b128 v[154:157], v1 offset:1024
	ds_read_b128 v[158:161], v1 offset:2048
	ds_read_b128 v[186:189], v1 offset:3072
	v_lshl_add_u64 v[36:37], s[18:19], 0, v[180:181]
	s_add_i32 m0, s29, 0xc000
	ds_read_b128 v[190:193], v185
	ds_read_b128 v[194:197], v185 offset:1024
	ds_read_b128 v[198:201], v185 offset:2048
	ds_read_b128 v[202:205], v185 offset:3072
	ds_read_b128 v[206:209], v185 offset:4096
	ds_read_b128 v[210:213], v185 offset:5120
	ds_read_b128 v[214:217], v185 offset:6144
	ds_read_b128 v[232:235], v185 offset:7168
	global_load_lds_dwordx4 v[36:37], off
	v_lshl_add_u64 v[36:37], s[18:19], 0, v[178:179]
	s_add_i32 m0, s29, 0xe000
	s_nop 0
	global_load_lds_dwordx4 v[36:37], off
	s_waitcnt vmcnt(8)
	s_waitcnt lgkmcnt(0)
	s_barrier
	s_setprio 1
	s_waitcnt lgkmcnt(0)
	v_mfma_f32_16x16x32_bf16 v[130:133], v[134:137], v[190:193], v[130:133]
	v_mfma_f32_16x16x32_bf16 v[126:129], v[142:145], v[190:193], v[126:129]
	v_mfma_f32_16x16x32_bf16 v[122:125], v[134:137], v[198:201], v[122:125]
	v_mfma_f32_16x16x32_bf16 v[118:121], v[142:145], v[198:201], v[118:121]
	v_mfma_f32_16x16x32_bf16 v[114:117], v[134:137], v[206:209], v[114:117]
	v_mfma_f32_16x16x32_bf16 v[110:113], v[142:145], v[206:209], v[110:113]
	v_mfma_f32_16x16x32_bf16 v[106:109], v[134:137], v[214:217], v[106:109]
	v_mfma_f32_16x16x32_bf16 v[102:105], v[142:145], v[214:217], v[102:105]
	v_mfma_f32_16x16x32_bf16 v[130:133], v[138:141], v[194:197], v[130:133]
	v_mfma_f32_16x16x32_bf16 v[126:129], v[146:149], v[194:197], v[126:129]
	v_mfma_f32_16x16x32_bf16 v[122:125], v[138:141], v[202:205], v[122:125]
	v_mfma_f32_16x16x32_bf16 v[118:121], v[146:149], v[202:205], v[118:121]
	v_mfma_f32_16x16x32_bf16 v[114:117], v[138:141], v[210:213], v[114:117]
	v_mfma_f32_16x16x32_bf16 v[110:113], v[146:149], v[210:213], v[110:113]
	v_mfma_f32_16x16x32_bf16 v[106:109], v[138:141], v[232:235], v[106:109]
	v_mfma_f32_16x16x32_bf16 v[102:105], v[146:149], v[232:235], v[102:105]
	v_mfma_f32_16x16x32_bf16 v[98:101], v[150:153], v[190:193], v[98:101]
	v_mfma_f32_16x16x32_bf16 v[94:97], v[158:161], v[190:193], v[94:97]
	v_mfma_f32_16x16x32_bf16 v[90:93], v[150:153], v[198:201], v[90:93]
	v_mfma_f32_16x16x32_bf16 v[86:89], v[158:161], v[198:201], v[86:89]
	v_mfma_f32_16x16x32_bf16 v[82:85], v[150:153], v[206:209], v[82:85]
	v_mfma_f32_16x16x32_bf16 v[78:81], v[158:161], v[206:209], v[78:81]
	v_mfma_f32_16x16x32_bf16 v[74:77], v[150:153], v[214:217], v[74:77]
	v_mfma_f32_16x16x32_bf16 v[70:73], v[158:161], v[214:217], v[70:73]
	v_mfma_f32_16x16x32_bf16 v[98:101], v[154:157], v[194:197], v[98:101]
	v_mfma_f32_16x16x32_bf16 v[94:97], v[186:189], v[194:197], v[94:97]
	v_mfma_f32_16x16x32_bf16 v[90:93], v[154:157], v[202:205], v[90:93]
	v_mfma_f32_16x16x32_bf16 v[86:89], v[186:189], v[202:205], v[86:89]
	v_mfma_f32_16x16x32_bf16 v[82:85], v[154:157], v[210:213], v[82:85]
	v_mfma_f32_16x16x32_bf16 v[78:81], v[186:189], v[210:213], v[78:81]
	v_mfma_f32_16x16x32_bf16 v[74:77], v[154:157], v[232:235], v[74:77]
	v_mfma_f32_16x16x32_bf16 v[70:73], v[186:189], v[232:235], v[70:73]
	s_setprio 0
	s_barrier
	s_add_i32 s18, s50, s28
	v_lshl_add_u64 v[220:221], s[22:23], 0, v[174:175]
	s_mov_b32 m0, s18
	ds_read_b128 v[190:193], v185 offset:16384
	ds_read_b128 v[194:197], v185 offset:17408
	ds_read_b128 v[198:201], v185 offset:18432
	ds_read_b128 v[202:205], v185 offset:19456
	ds_read_b128 v[206:209], v185 offset:20480
	ds_read_b128 v[210:213], v185 offset:21504
	ds_read_b128 v[214:217], v185 offset:22528
	ds_read_b128 v[232:235], v185 offset:23552
	global_load_lds_dwordx4 v[220:221], off
	s_add_i32 m0, s18, 0x2000
	s_add_u32 s18, s22, 0x180000
	v_lshl_add_u64 v[236:237], s[22:23], 0, v[162:163]
	s_addc_u32 s19, s23, 0
	s_add_i32 s50, s51, s28
	global_load_lds_dwordx4 v[236:237], off
	v_lshl_add_u64 v[36:37], s[18:19], 0, v[174:175]
	s_mov_b32 m0, s50
	v_lshl_add_u64 v[238:239], s[24:25], 0, v[176:177]
	global_load_lds_dwordx4 v[36:37], off
	v_lshl_add_u64 v[36:37], s[18:19], 0, v[162:163]
	s_add_i32 m0, s50, 0x2000
	v_lshl_add_u64 v[240:241], s[24:25], 0, v[172:173]
	global_load_lds_dwordx4 v[36:37], off
	s_mov_b32 m0, s29
	s_nop 0
	global_load_lds_dwordx4 v[238:239], off
	s_mov_b32 m0, s30
	s_nop 0
	global_load_lds_dwordx4 v[240:241], off
	s_waitcnt vmcnt(8)
	s_waitcnt lgkmcnt(0)
	s_barrier
	s_setprio 1
	s_waitcnt lgkmcnt(0)
	v_mfma_f32_16x16x32_bf16 v[66:69], v[134:137], v[190:193], v[66:69]
	v_mfma_f32_16x16x32_bf16 v[62:65], v[142:145], v[190:193], v[62:65]
	v_mfma_f32_16x16x32_bf16 v[58:61], v[134:137], v[198:201], v[58:61]
	v_mfma_f32_16x16x32_bf16 v[54:57], v[142:145], v[198:201], v[54:57]
	v_mfma_f32_16x16x32_bf16 v[50:53], v[134:137], v[206:209], v[50:53]
	v_mfma_f32_16x16x32_bf16 v[46:49], v[142:145], v[206:209], v[46:49]
	v_mfma_f32_16x16x32_bf16 v[42:45], v[134:137], v[214:217], v[42:45]
	v_mfma_f32_16x16x32_bf16 v[36:39], v[142:145], v[214:217], v[38:41]
	v_mfma_f32_16x16x32_bf16 v[66:69], v[138:141], v[194:197], v[66:69]
	v_mfma_f32_16x16x32_bf16 v[62:65], v[146:149], v[194:197], v[62:65]
	v_mfma_f32_16x16x32_bf16 v[58:61], v[138:141], v[202:205], v[58:61]
	v_mfma_f32_16x16x32_bf16 v[54:57], v[146:149], v[202:205], v[54:57]
	v_mfma_f32_16x16x32_bf16 v[50:53], v[138:141], v[210:213], v[50:53]
	v_mfma_f32_16x16x32_bf16 v[46:49], v[146:149], v[210:213], v[46:49]
	v_mfma_f32_16x16x32_bf16 v[42:45], v[138:141], v[232:235], v[42:45]
	v_mfma_f32_16x16x32_bf16 v[36:39], v[146:149], v[232:235], v[36:39]
	v_mfma_f32_16x16x32_bf16 v[30:33], v[150:153], v[190:193], v[30:33]
	v_mfma_f32_16x16x32_bf16 v[26:29], v[158:161], v[190:193], v[26:29]
	v_mfma_f32_16x16x32_bf16 v[22:25], v[150:153], v[198:201], v[22:25]
	v_mfma_f32_16x16x32_bf16 v[18:21], v[158:161], v[198:201], v[18:21]
	v_mfma_f32_16x16x32_bf16 v[14:17], v[150:153], v[206:209], v[14:17]
	v_mfma_f32_16x16x32_bf16 v[10:13], v[158:161], v[206:209], v[10:13]
	v_mfma_f32_16x16x32_bf16 v[6:9], v[150:153], v[214:217], v[6:9]
	v_mfma_f32_16x16x32_bf16 v[2:5], v[158:161], v[214:217], v[2:5]
	v_mfma_f32_16x16x32_bf16 v[30:33], v[154:157], v[194:197], v[30:33]
	v_mfma_f32_16x16x32_bf16 v[26:29], v[186:189], v[194:197], v[26:29]
	v_mfma_f32_16x16x32_bf16 v[22:25], v[154:157], v[202:205], v[22:25]
	v_mfma_f32_16x16x32_bf16 v[18:21], v[186:189], v[202:205], v[18:21]
	v_mfma_f32_16x16x32_bf16 v[14:17], v[154:157], v[210:213], v[14:17]
	v_mfma_f32_16x16x32_bf16 v[10:13], v[186:189], v[210:213], v[10:13]
	v_mfma_f32_16x16x32_bf16 v[6:9], v[154:157], v[232:235], v[6:9]
	v_mfma_f32_16x16x32_bf16 v[2:5], v[186:189], v[232:235], v[2:5]
	s_setprio 0
	s_barrier
	s_add_i32 s50, 0, 0x18000
	v_add_u32_e32 v1, s50, v184
	s_add_i32 s51, 0, 0x1c000
	ds_read_b128 v[134:137], v1
	ds_read_b128 v[138:141], v1 offset:1024
	ds_read_b128 v[142:145], v1 offset:2048
	ds_read_b128 v[146:149], v1 offset:3072
	v_add_u32_e32 v1, s51, v184
	ds_read_b128 v[150:153], v1
	ds_read_b128 v[154:157], v1 offset:1024
	ds_read_b128 v[158:161], v1 offset:2048
	ds_read_b128 v[186:189], v1 offset:3072
	s_add_u32 s18, s24, 0x180000
	s_addc_u32 s19, s25, 0
	s_mov_b32 m0, s31
	v_lshl_add_u64 v[40:41], s[18:19], 0, v[176:177]
	ds_read_b128 v[190:193], v185 offset:32768
	ds_read_b128 v[194:197], v185 offset:33792
	ds_read_b128 v[198:201], v185 offset:34816
	ds_read_b128 v[202:205], v185 offset:35840
	ds_read_b128 v[206:209], v185 offset:36864
	ds_read_b128 v[210:213], v185 offset:37888
	ds_read_b128 v[214:217], v185 offset:38912
	ds_read_b128 v[232:235], v185 offset:39936
	global_load_lds_dwordx4 v[40:41], off
	v_lshl_add_u64 v[40:41], s[18:19], 0, v[172:173]
	s_mov_b32 m0, s34
	s_nop 0
	global_load_lds_dwordx4 v[40:41], off
	s_waitcnt vmcnt(8)
	s_waitcnt lgkmcnt(0)
	s_barrier
	s_setprio 1
	s_waitcnt lgkmcnt(0)
	v_mfma_f32_16x16x32_bf16 v[130:133], v[134:137], v[190:193], v[130:133]
	v_mfma_f32_16x16x32_bf16 v[126:129], v[142:145], v[190:193], v[126:129]
	v_mfma_f32_16x16x32_bf16 v[122:125], v[134:137], v[198:201], v[122:125]
	v_mfma_f32_16x16x32_bf16 v[118:121], v[142:145], v[198:201], v[118:121]
	v_mfma_f32_16x16x32_bf16 v[114:117], v[134:137], v[206:209], v[114:117]
	v_mfma_f32_16x16x32_bf16 v[110:113], v[142:145], v[206:209], v[110:113]
	v_mfma_f32_16x16x32_bf16 v[106:109], v[134:137], v[214:217], v[106:109]
	v_mfma_f32_16x16x32_bf16 v[102:105], v[142:145], v[214:217], v[102:105]
	v_mfma_f32_16x16x32_bf16 v[130:133], v[138:141], v[194:197], v[130:133]
	v_mfma_f32_16x16x32_bf16 v[126:129], v[146:149], v[194:197], v[126:129]
	v_mfma_f32_16x16x32_bf16 v[122:125], v[138:141], v[202:205], v[122:125]
	v_mfma_f32_16x16x32_bf16 v[118:121], v[146:149], v[202:205], v[118:121]
	v_mfma_f32_16x16x32_bf16 v[114:117], v[138:141], v[210:213], v[114:117]
	v_mfma_f32_16x16x32_bf16 v[110:113], v[146:149], v[210:213], v[110:113]
	v_mfma_f32_16x16x32_bf16 v[106:109], v[138:141], v[232:235], v[106:109]
	v_mfma_f32_16x16x32_bf16 v[102:105], v[146:149], v[232:235], v[102:105]
	v_mfma_f32_16x16x32_bf16 v[98:101], v[150:153], v[190:193], v[98:101]
	v_mfma_f32_16x16x32_bf16 v[94:97], v[158:161], v[190:193], v[94:97]
	v_mfma_f32_16x16x32_bf16 v[90:93], v[150:153], v[198:201], v[90:93]
	v_mfma_f32_16x16x32_bf16 v[86:89], v[158:161], v[198:201], v[86:89]
	v_mfma_f32_16x16x32_bf16 v[82:85], v[150:153], v[206:209], v[82:85]
	v_mfma_f32_16x16x32_bf16 v[78:81], v[158:161], v[206:209], v[78:81]
	v_mfma_f32_16x16x32_bf16 v[74:77], v[150:153], v[214:217], v[74:77]
	v_mfma_f32_16x16x32_bf16 v[70:73], v[158:161], v[214:217], v[70:73]
	v_mfma_f32_16x16x32_bf16 v[98:101], v[154:157], v[194:197], v[98:101]
	v_mfma_f32_16x16x32_bf16 v[94:97], v[186:189], v[194:197], v[94:97]
	v_mfma_f32_16x16x32_bf16 v[90:93], v[154:157], v[202:205], v[90:93]
	v_mfma_f32_16x16x32_bf16 v[86:89], v[186:189], v[202:205], v[86:89]
	v_mfma_f32_16x16x32_bf16 v[82:85], v[154:157], v[210:213], v[82:85]
	v_mfma_f32_16x16x32_bf16 v[78:81], v[186:189], v[210:213], v[78:81]
	v_mfma_f32_16x16x32_bf16 v[74:77], v[154:157], v[232:235], v[74:77]
	v_mfma_f32_16x16x32_bf16 v[70:73], v[186:189], v[232:235], v[70:73]
	s_setprio 0
	s_barrier
	s_add_i32 s18, s50, s28
	v_lshl_add_u64 v[40:41], v[220:221], 0, s[2:3]
	s_mov_b32 m0, s18
	ds_read_b128 v[190:193], v185 offset:49152
	ds_read_b128 v[194:197], v185 offset:50176
	ds_read_b128 v[198:201], v185 offset:51200
	ds_read_b128 v[202:205], v185 offset:52224
	ds_read_b128 v[206:209], v185 offset:53248
	ds_read_b128 v[210:213], v185 offset:54272
	ds_read_b128 v[214:217], v185 offset:55296
	ds_read_b128 v[232:235], v185 offset:56320
	global_load_lds_dwordx4 v[40:41], off
	s_add_i32 m0, s18, 0x2000
	s_add_u32 s18, s22, 0x180080
	v_lshl_add_u64 v[40:41], v[236:237], 0, s[2:3]
	s_addc_u32 s19, s23, 0
	s_add_i32 s22, s51, s28
	global_load_lds_dwordx4 v[40:41], off
	v_lshl_add_u64 v[40:41], s[18:19], 0, v[174:175]
	s_mov_b32 m0, s22
	s_nop 0
	global_load_lds_dwordx4 v[40:41], off
	v_lshl_add_u64 v[40:41], s[18:19], 0, v[162:163]
	s_add_i32 m0, s22, 0x2000
	s_nop 0
	global_load_lds_dwordx4 v[40:41], off
	v_lshl_add_u64 v[40:41], v[238:239], 0, s[2:3]
	s_mov_b32 m0, s42
	s_nop 0
	global_load_lds_dwordx4 v[40:41], off
	v_lshl_add_u64 v[40:41], v[240:241], 0, s[2:3]
	s_mov_b32 m0, s43
	s_nop 0
	global_load_lds_dwordx4 v[40:41], off
	s_waitcnt vmcnt(8)
	s_waitcnt lgkmcnt(0)
	s_barrier
	s_setprio 1
	s_waitcnt lgkmcnt(0)
	v_mfma_f32_16x16x32_bf16 v[66:69], v[134:137], v[190:193], v[66:69]
	v_mfma_f32_16x16x32_bf16 v[62:65], v[142:145], v[190:193], v[62:65]
	v_mfma_f32_16x16x32_bf16 v[58:61], v[134:137], v[198:201], v[58:61]
	v_mfma_f32_16x16x32_bf16 v[54:57], v[142:145], v[198:201], v[54:57]
	v_mfma_f32_16x16x32_bf16 v[50:53], v[134:137], v[206:209], v[50:53]
	v_mfma_f32_16x16x32_bf16 v[46:49], v[142:145], v[206:209], v[46:49]
	v_mfma_f32_16x16x32_bf16 v[40:43], v[134:137], v[214:217], v[42:45]
	v_mfma_f32_16x16x32_bf16 v[36:39], v[142:145], v[214:217], v[36:39]
	v_mfma_f32_16x16x32_bf16 v[66:69], v[138:141], v[194:197], v[66:69]
	v_mfma_f32_16x16x32_bf16 v[62:65], v[146:149], v[194:197], v[62:65]
	v_mfma_f32_16x16x32_bf16 v[58:61], v[138:141], v[202:205], v[58:61]
	v_mfma_f32_16x16x32_bf16 v[54:57], v[146:149], v[202:205], v[54:57]
	v_mfma_f32_16x16x32_bf16 v[50:53], v[138:141], v[210:213], v[50:53]
	v_mfma_f32_16x16x32_bf16 v[46:49], v[146:149], v[210:213], v[46:49]
	v_mfma_f32_16x16x32_bf16 v[42:45], v[138:141], v[232:235], v[40:43]
	v_mfma_f32_16x16x32_bf16 v[38:41], v[146:149], v[232:235], v[36:39]
	v_mfma_f32_16x16x32_bf16 v[30:33], v[150:153], v[190:193], v[30:33]
	v_mfma_f32_16x16x32_bf16 v[26:29], v[158:161], v[190:193], v[26:29]
	v_mfma_f32_16x16x32_bf16 v[22:25], v[150:153], v[198:201], v[22:25]
	v_mfma_f32_16x16x32_bf16 v[18:21], v[158:161], v[198:201], v[18:21]
	v_mfma_f32_16x16x32_bf16 v[14:17], v[150:153], v[206:209], v[14:17]
	v_mfma_f32_16x16x32_bf16 v[10:13], v[158:161], v[206:209], v[10:13]
	v_mfma_f32_16x16x32_bf16 v[6:9], v[150:153], v[214:217], v[6:9]
	v_mfma_f32_16x16x32_bf16 v[2:5], v[158:161], v[214:217], v[2:5]
	v_mfma_f32_16x16x32_bf16 v[30:33], v[154:157], v[194:197], v[30:33]
	v_mfma_f32_16x16x32_bf16 v[26:29], v[186:189], v[194:197], v[26:29]
	v_mfma_f32_16x16x32_bf16 v[22:25], v[154:157], v[202:205], v[22:25]
	v_mfma_f32_16x16x32_bf16 v[18:21], v[186:189], v[202:205], v[18:21]
	v_mfma_f32_16x16x32_bf16 v[14:17], v[154:157], v[210:213], v[14:17]
	v_mfma_f32_16x16x32_bf16 v[10:13], v[186:189], v[210:213], v[10:13]
	v_mfma_f32_16x16x32_bf16 v[6:9], v[154:157], v[232:235], v[6:9]
	v_mfma_f32_16x16x32_bf16 v[2:5], v[186:189], v[232:235], v[2:5]
	s_setprio 0
	s_barrier
	s_add_i32 s41, s41, 2
	s_add_u32 s13, s13, 0x100
	s_addc_u32 s40, s40, 0
	s_cmp_gt_u32 s41, 29
	s_mov_b64 s[18:19], s[20:21]
	s_cbranch_scc0 .LBB0_1624
	s_and_b64 vcc, exec, s[10:11]
	s_cbranch_vccz .LBB0_1627
	s_barrier

.LBB0_1732:
	s_add_u32 s20, s18, 0xfff00080
	s_addc_u32 s21, s19, -1
	s_add_i32 s47, 0, 0x10000
	s_cmp_eq_u32 s46, 60
	s_cselect_b32 s23, s13, s21
	s_cselect_b32 s22, s42, s20
	v_add_u32_e32 v1, s47, v144
	s_cselect_b32 s21, s11, s45
	s_cselect_b32 s20, s43, s44
	s_add_i32 s50, 0, 0x14000
	ds_read_b128 v[148:151], v1
	ds_read_b128 v[152:155], v1 offset:1024
	ds_read_b128 v[156:159], v1 offset:2048
	ds_read_b128 v[160:163], v1 offset:3072
	v_add_u32_e32 v1, s50, v144
	ds_read_b128 v[172:175], v1
	ds_read_b128 v[176:179], v1 offset:1024
	ds_read_b128 v[180:183], v1 offset:2048
	ds_read_b128 v[184:187], v1 offset:3072
	v_lshl_add_u64 v[216:217], s[18:19], 0, v[142:143]
	s_add_i32 m0, s29, 0xc000
	ds_read_b128 v[188:191], v146
	ds_read_b128 v[192:195], v146 offset:1024
	ds_read_b128 v[196:199], v146 offset:2048
	ds_read_b128 v[200:203], v146 offset:3072
	ds_read_b128 v[204:207], v146 offset:4096
	ds_read_b128 v[208:211], v146 offset:5120
	ds_read_b128 v[212:215], v146 offset:6144
	ds_read_b128 v[232:235], v146 offset:7168
	global_load_lds_dwordx4 v[216:217], off
	v_lshl_add_u64 v[216:217], s[18:19], 0, v[140:141]
	s_add_i32 m0, s29, 0xe000
	s_nop 0
	global_load_lds_dwordx4 v[216:217], off
	s_waitcnt vmcnt(8)
	s_waitcnt lgkmcnt(0)
	s_barrier
	s_setprio 1
	s_waitcnt lgkmcnt(0)
	v_mfma_f32_16x16x32_bf16 v[128:131], v[148:151], v[188:191], v[128:131]
	v_mfma_f32_16x16x32_bf16 v[124:127], v[156:159], v[188:191], v[124:127]
	v_mfma_f32_16x16x32_bf16 v[120:123], v[148:151], v[196:199], v[120:123]
	v_mfma_f32_16x16x32_bf16 v[116:119], v[156:159], v[196:199], v[116:119]
	v_mfma_f32_16x16x32_bf16 v[104:107], v[148:151], v[204:207], v[104:107]
	v_mfma_f32_16x16x32_bf16 v[100:103], v[156:159], v[204:207], v[100:103]
	v_mfma_f32_16x16x32_bf16 v[88:91], v[148:151], v[212:215], v[88:91]
	v_mfma_f32_16x16x32_bf16 v[84:87], v[156:159], v[212:215], v[84:87]
	v_mfma_f32_16x16x32_bf16 v[128:131], v[152:155], v[192:195], v[128:131]
	v_mfma_f32_16x16x32_bf16 v[124:127], v[160:163], v[192:195], v[124:127]
	v_mfma_f32_16x16x32_bf16 v[120:123], v[152:155], v[200:203], v[120:123]
	v_mfma_f32_16x16x32_bf16 v[116:119], v[160:163], v[200:203], v[116:119]
	v_mfma_f32_16x16x32_bf16 v[104:107], v[152:155], v[208:211], v[104:107]
	v_mfma_f32_16x16x32_bf16 v[100:103], v[160:163], v[208:211], v[100:103]
	v_mfma_f32_16x16x32_bf16 v[88:91], v[152:155], v[232:235], v[88:91]
	v_mfma_f32_16x16x32_bf16 v[84:87], v[160:163], v[232:235], v[84:87]
	v_mfma_f32_16x16x32_bf16 v[112:115], v[172:175], v[188:191], v[112:115]
	v_mfma_f32_16x16x32_bf16 v[108:111], v[180:183], v[188:191], v[108:111]
	v_mfma_f32_16x16x32_bf16 v[96:99], v[172:175], v[196:199], v[96:99]
	v_mfma_f32_16x16x32_bf16 v[92:95], v[180:183], v[196:199], v[92:95]
	v_mfma_f32_16x16x32_bf16 v[80:83], v[172:175], v[204:207], v[80:83]
	v_mfma_f32_16x16x32_bf16 v[76:79], v[180:183], v[204:207], v[76:79]
	v_mfma_f32_16x16x32_bf16 v[72:75], v[172:175], v[212:215], v[72:75]
	v_mfma_f32_16x16x32_bf16 v[68:71], v[180:183], v[212:215], v[68:71]
	v_mfma_f32_16x16x32_bf16 v[112:115], v[176:179], v[192:195], v[112:115]
	v_mfma_f32_16x16x32_bf16 v[108:111], v[184:187], v[192:195], v[108:111]
	v_mfma_f32_16x16x32_bf16 v[96:99], v[176:179], v[200:203], v[96:99]
	v_mfma_f32_16x16x32_bf16 v[92:95], v[184:187], v[200:203], v[92:95]
	v_mfma_f32_16x16x32_bf16 v[80:83], v[176:179], v[208:211], v[80:83]
	v_mfma_f32_16x16x32_bf16 v[76:79], v[184:187], v[208:211], v[76:79]
	v_mfma_f32_16x16x32_bf16 v[72:75], v[176:179], v[232:235], v[72:75]
	v_mfma_f32_16x16x32_bf16 v[68:71], v[184:187], v[232:235], v[68:71]
	s_setprio 0
	s_barrier
	s_add_i32 s47, s47, s26
	v_lshl_add_u64 v[216:217], s[20:21], 0, v[136:137]
	s_mov_b32 m0, s47
	ds_read_b128 v[188:191], v146 offset:16384
	ds_read_b128 v[192:195], v146 offset:17408
	ds_read_b128 v[196:199], v146 offset:18432
	ds_read_b128 v[200:203], v146 offset:19456
	ds_read_b128 v[204:207], v146 offset:20480
	ds_read_b128 v[208:211], v146 offset:21504
	ds_read_b128 v[212:215], v146 offset:22528
	ds_read_b128 v[232:235], v146 offset:23552
	global_load_lds_dwordx4 v[216:217], off
	s_add_i32 m0, s47, 0x2000
	s_add_u32 s48, s20, 0x100000
	v_lshl_add_u64 v[220:221], s[20:21], 0, v[132:133]
	s_addc_u32 s49, s21, 0
	s_add_i32 s47, s50, s26
	global_load_lds_dwordx4 v[220:221], off
	v_lshl_add_u64 v[236:237], s[48:49], 0, v[136:137]
	s_mov_b32 m0, s47
	v_lshl_add_u64 v[238:239], s[22:23], 0, v[134:135]
	global_load_lds_dwordx4 v[236:237], off
	v_lshl_add_u64 v[236:237], s[48:49], 0, v[132:133]
	s_add_i32 m0, s47, 0x2000
	s_nop 0
	global_load_lds_dwordx4 v[236:237], off
	v_lshl_add_u64 v[236:237], s[22:23], 0, v[138:139]
	s_mov_b32 m0, s29
	s_nop 0
	global_load_lds_dwordx4 v[236:237], off
	s_mov_b32 m0, s30
	s_nop 0
	global_load_lds_dwordx4 v[238:239], off
	s_waitcnt vmcnt(8)
	s_waitcnt lgkmcnt(0)
	s_barrier
	s_setprio 1
	s_waitcnt lgkmcnt(0)
	v_mfma_f32_16x16x32_bf16 v[60:63], v[148:151], v[188:191], v[60:63]
	v_mfma_f32_16x16x32_bf16 v[56:59], v[156:159], v[188:191], v[56:59]
	v_mfma_f32_16x16x32_bf16 v[44:47], v[148:151], v[196:199], v[44:47]
	v_mfma_f32_16x16x32_bf16 v[40:43], v[156:159], v[196:199], v[40:43]
	v_mfma_f32_16x16x32_bf16 v[26:29], v[148:151], v[204:207], v[26:29]
	v_mfma_f32_16x16x32_bf16 v[22:25], v[156:159], v[204:207], v[22:25]
	v_mfma_f32_16x16x32_bf16 v[10:13], v[148:151], v[212:215], v[10:13]
	v_mfma_f32_16x16x32_bf16 v[6:9], v[156:159], v[212:215], v[6:9]
	v_mfma_f32_16x16x32_bf16 v[60:63], v[152:155], v[192:195], v[60:63]
	v_mfma_f32_16x16x32_bf16 v[56:59], v[160:163], v[192:195], v[56:59]
	v_mfma_f32_16x16x32_bf16 v[44:47], v[152:155], v[200:203], v[44:47]
	v_mfma_f32_16x16x32_bf16 v[40:43], v[160:163], v[200:203], v[40:43]
	v_mfma_f32_16x16x32_bf16 v[26:29], v[152:155], v[208:211], v[26:29]
	v_mfma_f32_16x16x32_bf16 v[22:25], v[160:163], v[208:211], v[22:25]
	v_mfma_f32_16x16x32_bf16 v[10:13], v[152:155], v[232:235], v[10:13]
	v_mfma_f32_16x16x32_bf16 v[6:9], v[160:163], v[232:235], v[6:9]
	v_mfma_f32_16x16x32_bf16 v[36:39], v[172:175], v[188:191], v[36:39]
	v_mfma_f32_16x16x32_bf16 v[30:33], v[180:183], v[188:191], v[30:33]
	v_mfma_f32_16x16x32_bf16 v[18:21], v[172:175], v[196:199], v[18:21]
	v_mfma_f32_16x16x32_bf16 v[14:17], v[180:183], v[196:199], v[14:17]
	v_mfma_f32_16x16x32_bf16 v[2:5], v[172:175], v[204:207], v[2:5]
	v_mfma_f32_16x16x32_bf16 v[64:67], v[180:183], v[204:207], v[64:67]
	v_mfma_f32_16x16x32_bf16 v[48:51], v[172:175], v[212:215], v[48:51]
	v_mfma_f32_16x16x32_bf16 v[52:55], v[180:183], v[212:215], v[52:55]
	v_mfma_f32_16x16x32_bf16 v[36:39], v[176:179], v[192:195], v[36:39]
	v_mfma_f32_16x16x32_bf16 v[30:33], v[184:187], v[192:195], v[30:33]
	v_mfma_f32_16x16x32_bf16 v[18:21], v[176:179], v[200:203], v[18:21]
	v_mfma_f32_16x16x32_bf16 v[14:17], v[184:187], v[200:203], v[14:17]
	v_mfma_f32_16x16x32_bf16 v[2:5], v[176:179], v[208:211], v[2:5]
	v_mfma_f32_16x16x32_bf16 v[64:67], v[184:187], v[208:211], v[64:67]
	v_mfma_f32_16x16x32_bf16 v[48:51], v[176:179], v[232:235], v[48:51]
	v_mfma_f32_16x16x32_bf16 v[52:55], v[184:187], v[232:235], v[52:55]
	s_setprio 0
	s_barrier
	s_add_i32 s47, 0, 0x18000
	v_add_u32_e32 v1, s47, v144
	s_add_i32 s48, 0, 0x1c000
	ds_read_b128 v[148:151], v1
	ds_read_b128 v[152:155], v1 offset:1024
	ds_read_b128 v[156:159], v1 offset:2048
	ds_read_b128 v[160:163], v1 offset:3072
	v_add_u32_e32 v1, s48, v144
	ds_read_b128 v[172:175], v1
	ds_read_b128 v[176:179], v1 offset:1024
	ds_read_b128 v[180:183], v1 offset:2048
	ds_read_b128 v[184:187], v1 offset:3072
	s_add_u32 s22, s22, 0x100000
	s_addc_u32 s23, s23, 0
	s_mov_b32 m0, s31
	v_lshl_add_u64 v[240:241], s[22:23], 0, v[138:139]
	ds_read_b128 v[188:191], v146 offset:32768
	ds_read_b128 v[192:195], v146 offset:33792
	ds_read_b128 v[196:199], v146 offset:34816
	ds_read_b128 v[200:203], v146 offset:35840
	ds_read_b128 v[204:207], v146 offset:36864
	ds_read_b128 v[208:211], v146 offset:37888
	ds_read_b128 v[212:215], v146 offset:38912
	ds_read_b128 v[232:235], v146 offset:39936
	global_load_lds_dwordx4 v[240:241], off
	v_lshl_add_u64 v[240:241], s[22:23], 0, v[134:135]
	s_mov_b32 m0, s34
	s_nop 0
	global_load_lds_dwordx4 v[240:241], off
	s_waitcnt vmcnt(8)
	s_waitcnt lgkmcnt(0)
	s_barrier
	s_setprio 1
	s_waitcnt lgkmcnt(0)
	v_mfma_f32_16x16x32_bf16 v[128:131], v[148:151], v[188:191], v[128:131]
	v_mfma_f32_16x16x32_bf16 v[124:127], v[156:159], v[188:191], v[124:127]
	v_mfma_f32_16x16x32_bf16 v[120:123], v[148:151], v[196:199], v[120:123]
	v_mfma_f32_16x16x32_bf16 v[116:119], v[156:159], v[196:199], v[116:119]
	v_mfma_f32_16x16x32_bf16 v[104:107], v[148:151], v[204:207], v[104:107]
	v_mfma_f32_16x16x32_bf16 v[100:103], v[156:159], v[204:207], v[100:103]
	v_mfma_f32_16x16x32_bf16 v[88:91], v[148:151], v[212:215], v[88:91]
	v_mfma_f32_16x16x32_bf16 v[84:87], v[156:159], v[212:215], v[84:87]
	v_mfma_f32_16x16x32_bf16 v[128:131], v[152:155], v[192:195], v[128:131]
	v_mfma_f32_16x16x32_bf16 v[124:127], v[160:163], v[192:195], v[124:127]
	v_mfma_f32_16x16x32_bf16 v[120:123], v[152:155], v[200:203], v[120:123]
	v_mfma_f32_16x16x32_bf16 v[116:119], v[160:163], v[200:203], v[116:119]
	v_mfma_f32_16x16x32_bf16 v[104:107], v[152:155], v[208:211], v[104:107]
	v_mfma_f32_16x16x32_bf16 v[100:103], v[160:163], v[208:211], v[100:103]
	v_mfma_f32_16x16x32_bf16 v[88:91], v[152:155], v[232:235], v[88:91]
	v_mfma_f32_16x16x32_bf16 v[84:87], v[160:163], v[232:235], v[84:87]
	v_mfma_f32_16x16x32_bf16 v[112:115], v[172:175], v[188:191], v[112:115]
	v_mfma_f32_16x16x32_bf16 v[108:111], v[180:183], v[188:191], v[108:111]
	v_mfma_f32_16x16x32_bf16 v[96:99], v[172:175], v[196:199], v[96:99]
	v_mfma_f32_16x16x32_bf16 v[92:95], v[180:183], v[196:199], v[92:95]
	v_mfma_f32_16x16x32_bf16 v[80:83], v[172:175], v[204:207], v[80:83]
	v_mfma_f32_16x16x32_bf16 v[76:79], v[180:183], v[204:207], v[76:79]
	v_mfma_f32_16x16x32_bf16 v[72:75], v[172:175], v[212:215], v[72:75]
	v_mfma_f32_16x16x32_bf16 v[68:71], v[180:183], v[212:215], v[68:71]
	v_mfma_f32_16x16x32_bf16 v[112:115], v[176:179], v[192:195], v[112:115]
	v_mfma_f32_16x16x32_bf16 v[108:111], v[184:187], v[192:195], v[108:111]
	v_mfma_f32_16x16x32_bf16 v[96:99], v[176:179], v[200:203], v[96:99]
	v_mfma_f32_16x16x32_bf16 v[92:95], v[184:187], v[200:203], v[92:95]
	v_mfma_f32_16x16x32_bf16 v[80:83], v[176:179], v[208:211], v[80:83]
	v_mfma_f32_16x16x32_bf16 v[76:79], v[184:187], v[208:211], v[76:79]
	v_mfma_f32_16x16x32_bf16 v[72:75], v[176:179], v[232:235], v[72:75]
	v_mfma_f32_16x16x32_bf16 v[68:71], v[184:187], v[232:235], v[68:71]
	s_setprio 0
	s_barrier
	s_add_i32 s22, s47, s26
	v_lshl_add_u64 v[216:217], v[216:217], 0, s[2:3]
	s_mov_b32 m0, s22
	ds_read_b128 v[188:191], v146 offset:49152
	ds_read_b128 v[192:195], v146 offset:50176
	ds_read_b128 v[196:199], v146 offset:51200
	ds_read_b128 v[200:203], v146 offset:52224
	ds_read_b128 v[204:207], v146 offset:53248
	ds_read_b128 v[208:211], v146 offset:54272
	ds_read_b128 v[212:215], v146 offset:55296
	ds_read_b128 v[232:235], v146 offset:56320
	global_load_lds_dwordx4 v[216:217], off
	s_add_i32 m0, s22, 0x2000
	s_add_u32 s20, s20, 0x100080
	v_lshl_add_u64 v[216:217], v[220:221], 0, s[2:3]
	s_addc_u32 s21, s21, 0
	s_add_i32 s22, s48, s26
	global_load_lds_dwordx4 v[216:217], off
	v_lshl_add_u64 v[216:217], s[20:21], 0, v[136:137]
	s_mov_b32 m0, s22
	s_nop 0
	global_load_lds_dwordx4 v[216:217], off
	v_lshl_add_u64 v[216:217], s[20:21], 0, v[132:133]
	s_add_i32 m0, s22, 0x2000
	s_nop 0
	global_load_lds_dwordx4 v[216:217], off
	v_lshl_add_u64 v[216:217], v[236:237], 0, s[2:3]
	s_mov_b32 m0, s35
	s_nop 0
	global_load_lds_dwordx4 v[216:217], off
	v_lshl_add_u64 v[216:217], v[238:239], 0, s[2:3]
	s_mov_b32 m0, s38
	s_nop 0
	global_load_lds_dwordx4 v[216:217], off
	s_waitcnt vmcnt(8)
	s_waitcnt lgkmcnt(0)
	s_barrier
	s_setprio 1
	s_waitcnt lgkmcnt(0)
	v_mfma_f32_16x16x32_bf16 v[60:63], v[148:151], v[188:191], v[60:63]
	v_mfma_f32_16x16x32_bf16 v[56:59], v[156:159], v[188:191], v[56:59]
	v_mfma_f32_16x16x32_bf16 v[44:47], v[148:151], v[196:199], v[44:47]
	v_mfma_f32_16x16x32_bf16 v[40:43], v[156:159], v[196:199], v[40:43]
	v_mfma_f32_16x16x32_bf16 v[26:29], v[148:151], v[204:207], v[26:29]
	v_mfma_f32_16x16x32_bf16 v[22:25], v[156:159], v[204:207], v[22:25]
	v_mfma_f32_16x16x32_bf16 v[10:13], v[148:151], v[212:215], v[10:13]
	v_mfma_f32_16x16x32_bf16 v[6:9], v[156:159], v[212:215], v[6:9]
	v_mfma_f32_16x16x32_bf16 v[60:63], v[152:155], v[192:195], v[60:63]
	v_mfma_f32_16x16x32_bf16 v[56:59], v[160:163], v[192:195], v[56:59]
	v_mfma_f32_16x16x32_bf16 v[44:47], v[152:155], v[200:203], v[44:47]
	v_mfma_f32_16x16x32_bf16 v[40:43], v[160:163], v[200:203], v[40:43]
	v_mfma_f32_16x16x32_bf16 v[26:29], v[152:155], v[208:211], v[26:29]
	v_mfma_f32_16x16x32_bf16 v[22:25], v[160:163], v[208:211], v[22:25]
	v_mfma_f32_16x16x32_bf16 v[10:13], v[152:155], v[232:235], v[10:13]
	v_mfma_f32_16x16x32_bf16 v[6:9], v[160:163], v[232:235], v[6:9]
	v_mfma_f32_16x16x32_bf16 v[36:39], v[172:175], v[188:191], v[36:39]
	v_mfma_f32_16x16x32_bf16 v[30:33], v[180:183], v[188:191], v[30:33]
	v_mfma_f32_16x16x32_bf16 v[18:21], v[172:175], v[196:199], v[18:21]
	v_mfma_f32_16x16x32_bf16 v[14:17], v[180:183], v[196:199], v[14:17]
	v_mfma_f32_16x16x32_bf16 v[2:5], v[172:175], v[204:207], v[2:5]
	v_mfma_f32_16x16x32_bf16 v[64:67], v[180:183], v[204:207], v[64:67]
	v_mfma_f32_16x16x32_bf16 v[48:51], v[172:175], v[212:215], v[48:51]
	v_mfma_f32_16x16x32_bf16 v[52:55], v[180:183], v[212:215], v[52:55]
	v_mfma_f32_16x16x32_bf16 v[36:39], v[176:179], v[192:195], v[36:39]
	v_mfma_f32_16x16x32_bf16 v[30:33], v[184:187], v[192:195], v[30:33]
	v_mfma_f32_16x16x32_bf16 v[18:21], v[176:179], v[200:203], v[18:21]
	v_mfma_f32_16x16x32_bf16 v[14:17], v[184:187], v[200:203], v[14:17]
	v_mfma_f32_16x16x32_bf16 v[2:5], v[176:179], v[208:211], v[2:5]
	v_mfma_f32_16x16x32_bf16 v[64:67], v[184:187], v[208:211], v[64:67]
	v_mfma_f32_16x16x32_bf16 v[48:51], v[176:179], v[232:235], v[48:51]
	v_mfma_f32_16x16x32_bf16 v[52:55], v[184:187], v[232:235], v[52:55]
	s_setprio 0
	s_barrier
	s_add_i32 s46, s46, 2
	s_add_u32 s44, s44, 0x100
	s_addc_u32 s45, s45, 0
	s_add_u32 s18, s18, 0x100
	s_addc_u32 s19, s19, 0
	s_cmp_gt_u32 s46, 61
	s_cbranch_scc0 .LBB0_1732
	s_and_b64 vcc, exec, s[8:9]
	s_cbranch_vccz .LBB0_1735
	s_barrier
